# v8: loader half setprio 3 (was 2)
# speedup vs baseline: 1.0059x; 1.0027x over previous
.LBB0_271:
	s_add_u32 s26, s14, 0xfffc0080
	s_addc_u32 s27, s15, -1
	s_add_i32 s54, 0, 0x10000
	s_cmp_eq_u32 s53, 12
	s_cselect_b32 s29, s21, s27
	s_cselect_b32 s28, s49, s26
	v_add_u32_e32 v154, s54, v141
	s_cselect_b32 s27, s19, s52
	s_cselect_b32 s26, s50, s51
	s_add_i32 s56, 0, 0x14000
	ds_read_b128 v[146:149], v154
	ds_read_b128 v[150:153], v154 offset:1024
	ds_read_b128 v[162:165], v154 offset:2048
	ds_read_b128 v[166:169], v154 offset:3072
	v_add_u32_e32 v154, s56, v141
	ds_read_b128 v[170:173], v154
	ds_read_b128 v[186:189], v154 offset:1024
	ds_read_b128 v[190:193], v154 offset:2048
	ds_read_b128 v[194:197], v154 offset:3072
	v_lshl_add_u64 v[154:155], s[14:15], 0, v[136:137]
	s_add_i32 m0, s37, 0xc000
	ds_read_b128 v[198:201], v145
	ds_read_b128 v[202:205], v145 offset:1024
	ds_read_b128 v[206:209], v145 offset:2048
	ds_read_b128 v[210:213], v145 offset:3072
	ds_read_b128 v[214:217], v145 offset:4096
	ds_read_b128 v[218:221], v145 offset:5120
	ds_read_b128 v[222:225], v145 offset:6144
	ds_read_b128 v[226:229], v145 offset:7168
	global_load_lds_dwordx4 v[154:155], off
	v_lshl_add_u64 v[154:155], s[14:15], 0, v[138:139]
	s_add_i32 m0, s37, 0xe000
	s_nop 0
	global_load_lds_dwordx4 v[154:155], off
	s_setprio 0
	s_waitcnt vmcnt(8)
	s_waitcnt lgkmcnt(0)
	s_barrier
	s_setprio 1
	v_mfma_f32_16x16x32_bf16 v[126:129], v[146:149], v[198:201], v[126:129]
	v_mfma_f32_16x16x32_bf16 v[122:125], v[162:165], v[198:201], v[122:125]
	v_mfma_f32_16x16x32_bf16 v[110:113], v[146:149], v[206:209], v[110:113]
	v_mfma_f32_16x16x32_bf16 v[106:109], v[162:165], v[206:209], v[106:109]
	v_mfma_f32_16x16x32_bf16 v[92:95], v[146:149], v[214:217], v[92:95]
	v_mfma_f32_16x16x32_bf16 v[88:91], v[162:165], v[214:217], v[88:91]
	v_mfma_f32_16x16x32_bf16 v[76:79], v[146:149], v[222:225], v[76:79]
	v_mfma_f32_16x16x32_bf16 v[72:75], v[162:165], v[222:225], v[72:75]
	v_mfma_f32_16x16x32_bf16 v[126:129], v[150:153], v[202:205], v[126:129]
	v_mfma_f32_16x16x32_bf16 v[122:125], v[166:169], v[202:205], v[122:125]
	v_mfma_f32_16x16x32_bf16 v[110:113], v[150:153], v[210:213], v[110:113]
	v_mfma_f32_16x16x32_bf16 v[106:109], v[166:169], v[210:213], v[106:109]
	v_mfma_f32_16x16x32_bf16 v[92:95], v[150:153], v[218:221], v[92:95]
	v_mfma_f32_16x16x32_bf16 v[88:91], v[166:169], v[218:221], v[88:91]
	v_mfma_f32_16x16x32_bf16 v[76:79], v[150:153], v[226:229], v[76:79]
	v_mfma_f32_16x16x32_bf16 v[72:75], v[166:169], v[226:229], v[72:75]
	s_setprio 0
	s_setprio 1
	v_mfma_f32_16x16x32_bf16 v[118:121], v[170:173], v[198:201], v[118:121]
	v_mfma_f32_16x16x32_bf16 v[114:117], v[190:193], v[198:201], v[114:117]
	v_mfma_f32_16x16x32_bf16 v[102:105], v[170:173], v[206:209], v[102:105]
	v_mfma_f32_16x16x32_bf16 v[98:101], v[190:193], v[206:209], v[98:101]
	v_mfma_f32_16x16x32_bf16 v[84:87], v[170:173], v[214:217], v[84:87]
	v_mfma_f32_16x16x32_bf16 v[80:83], v[190:193], v[214:217], v[80:83]
	v_mfma_f32_16x16x32_bf16 v[68:71], v[170:173], v[222:225], v[68:71]
	v_mfma_f32_16x16x32_bf16 v[64:67], v[190:193], v[222:225], v[64:67]
	v_mfma_f32_16x16x32_bf16 v[118:121], v[186:189], v[202:205], v[118:121]
	v_mfma_f32_16x16x32_bf16 v[114:117], v[194:197], v[202:205], v[114:117]
	v_mfma_f32_16x16x32_bf16 v[102:105], v[186:189], v[210:213], v[102:105]
	v_mfma_f32_16x16x32_bf16 v[98:101], v[194:197], v[210:213], v[98:101]
	v_mfma_f32_16x16x32_bf16 v[84:87], v[186:189], v[218:221], v[84:87]
	v_mfma_f32_16x16x32_bf16 v[80:83], v[194:197], v[218:221], v[80:83]
	v_mfma_f32_16x16x32_bf16 v[68:71], v[186:189], v[226:229], v[68:71]
	v_mfma_f32_16x16x32_bf16 v[64:67], v[194:197], v[226:229], v[64:67]
	s_setprio 0
	s_barrier
	s_setprio 3
	s_add_i32 s54, s54, s36
	v_lshl_add_u64 v[154:155], s[26:27], 0, v[96:97]
	s_mov_b32 m0, s54
	ds_read_b128 v[198:201], v145 offset:16384
	ds_read_b128 v[202:205], v145 offset:17408
	ds_read_b128 v[206:209], v145 offset:18432
	ds_read_b128 v[210:213], v145 offset:19456
	ds_read_b128 v[214:217], v145 offset:20480
	ds_read_b128 v[218:221], v145 offset:21504
	ds_read_b128 v[222:225], v145 offset:22528
	ds_read_b128 v[226:229], v145 offset:23552
	global_load_lds_dwordx4 v[154:155], off
	s_add_i32 m0, s54, 0x2000
	s_add_u32 s54, s26, 0x40000
	v_lshl_add_u64 v[156:157], s[26:27], 0, v[130:131]
	s_addc_u32 s55, s27, 0
	s_add_i32 s56, s56, s36
	global_load_lds_dwordx4 v[156:157], off
	v_lshl_add_u64 v[158:159], s[54:55], 0, v[96:97]
	s_mov_b32 m0, s56
	v_lshl_add_u64 v[182:183], s[28:29], 0, v[132:133]
	global_load_lds_dwordx4 v[158:159], off
	v_lshl_add_u64 v[158:159], s[54:55], 0, v[130:131]
	s_add_i32 m0, s56, 0x2000
	s_nop 0
	global_load_lds_dwordx4 v[158:159], off
	v_lshl_add_u64 v[158:159], s[28:29], 0, v[134:135]
	s_mov_b32 m0, s37
	s_nop 0
	global_load_lds_dwordx4 v[158:159], off
	s_mov_b32 m0, s38
	s_nop 0
	global_load_lds_dwordx4 v[182:183], off
	s_setprio 0
	s_waitcnt vmcnt(8)
	s_waitcnt lgkmcnt(0)
	s_barrier
	s_setprio 1
	v_mfma_f32_16x16x32_bf16 v[60:63], v[146:149], v[198:201], v[60:63]
	v_mfma_f32_16x16x32_bf16 v[56:59], v[162:165], v[198:201], v[56:59]
	v_mfma_f32_16x16x32_bf16 v[44:47], v[146:149], v[206:209], v[44:47]
	v_mfma_f32_16x16x32_bf16 v[40:43], v[162:165], v[206:209], v[40:43]
	v_mfma_f32_16x16x32_bf16 v[28:31], v[146:149], v[214:217], v[28:31]
	v_mfma_f32_16x16x32_bf16 v[24:27], v[162:165], v[214:217], v[24:27]
	v_mfma_f32_16x16x32_bf16 v[12:15], v[146:149], v[222:225], v[12:15]
	v_mfma_f32_16x16x32_bf16 v[4:7], v[162:165], v[222:225], v[4:7]
	v_mfma_f32_16x16x32_bf16 v[60:63], v[150:153], v[202:205], v[60:63]
	v_mfma_f32_16x16x32_bf16 v[56:59], v[166:169], v[202:205], v[56:59]
	v_mfma_f32_16x16x32_bf16 v[44:47], v[150:153], v[210:213], v[44:47]
	v_mfma_f32_16x16x32_bf16 v[40:43], v[166:169], v[210:213], v[40:43]
	v_mfma_f32_16x16x32_bf16 v[28:31], v[150:153], v[218:221], v[28:31]
	v_mfma_f32_16x16x32_bf16 v[24:27], v[166:169], v[218:221], v[24:27]
	v_mfma_f32_16x16x32_bf16 v[12:15], v[150:153], v[226:229], v[12:15]
	v_mfma_f32_16x16x32_bf16 v[4:7], v[166:169], v[226:229], v[4:7]
	s_setprio 0
	s_setprio 1
	v_mfma_f32_16x16x32_bf16 v[52:55], v[170:173], v[198:201], v[52:55]
	v_mfma_f32_16x16x32_bf16 v[48:51], v[190:193], v[198:201], v[48:51]
	v_mfma_f32_16x16x32_bf16 v[36:39], v[170:173], v[206:209], v[36:39]
	v_mfma_f32_16x16x32_bf16 v[32:35], v[190:193], v[206:209], v[32:35]
	v_mfma_f32_16x16x32_bf16 v[20:23], v[170:173], v[214:217], v[20:23]
	v_mfma_f32_16x16x32_bf16 v[16:19], v[190:193], v[214:217], v[16:19]
	v_mfma_f32_16x16x32_bf16 v[8:11], v[170:173], v[222:225], v[8:11]
	v_mfma_f32_16x16x32_bf16 v[0:3], v[190:193], v[222:225], v[0:3]
	v_mfma_f32_16x16x32_bf16 v[52:55], v[186:189], v[202:205], v[52:55]
	v_mfma_f32_16x16x32_bf16 v[48:51], v[194:197], v[202:205], v[48:51]
	v_mfma_f32_16x16x32_bf16 v[36:39], v[186:189], v[210:213], v[36:39]
	v_mfma_f32_16x16x32_bf16 v[32:35], v[194:197], v[210:213], v[32:35]
	v_mfma_f32_16x16x32_bf16 v[20:23], v[186:189], v[218:221], v[20:23]
	v_mfma_f32_16x16x32_bf16 v[16:19], v[194:197], v[218:221], v[16:19]
	v_mfma_f32_16x16x32_bf16 v[8:11], v[186:189], v[226:229], v[8:11]
	v_mfma_f32_16x16x32_bf16 v[0:3], v[194:197], v[226:229], v[0:3]
	s_setprio 0
	s_barrier
	s_setprio 3
	s_add_i32 s54, 0, 0x18000
	s_add_i32 s55, 0, 0x1c000
	v_add_u32_e32 v166, s54, v141
	v_add_u32_e32 v184, s55, v141
	ds_read_b128 v[146:149], v166
	ds_read_b128 v[150:153], v166 offset:1024
	ds_read_b128 v[162:165], v166 offset:2048
	ds_read_b128 v[166:169], v166 offset:3072
	ds_read_b128 v[170:173], v184
	ds_read_b128 v[186:189], v184 offset:1024
	ds_read_b128 v[190:193], v184 offset:2048
	ds_read_b128 v[194:197], v184 offset:3072
	s_add_u32 s28, s28, 0x40000
	s_addc_u32 s29, s29, 0
	s_mov_b32 m0, s39
	v_lshl_add_u64 v[184:185], s[28:29], 0, v[134:135]
	ds_read_b128 v[198:201], v145 offset:32768
	ds_read_b128 v[202:205], v145 offset:33792
	ds_read_b128 v[206:209], v145 offset:34816
	ds_read_b128 v[210:213], v145 offset:35840
	ds_read_b128 v[214:217], v145 offset:36864
	ds_read_b128 v[218:221], v145 offset:37888
	ds_read_b128 v[222:225], v145 offset:38912
	ds_read_b128 v[226:229], v145 offset:39936
	global_load_lds_dwordx4 v[184:185], off
	v_lshl_add_u64 v[184:185], s[28:29], 0, v[132:133]
	s_mov_b32 m0, s40
	s_nop 0
	global_load_lds_dwordx4 v[184:185], off
	s_setprio 0
	s_waitcnt vmcnt(8)
	s_waitcnt lgkmcnt(0)
	s_barrier
	s_setprio 1
	v_mfma_f32_16x16x32_bf16 v[126:129], v[146:149], v[198:201], v[126:129]
	v_mfma_f32_16x16x32_bf16 v[122:125], v[162:165], v[198:201], v[122:125]
	v_mfma_f32_16x16x32_bf16 v[110:113], v[146:149], v[206:209], v[110:113]
	v_mfma_f32_16x16x32_bf16 v[106:109], v[162:165], v[206:209], v[106:109]
	v_mfma_f32_16x16x32_bf16 v[92:95], v[146:149], v[214:217], v[92:95]
	v_mfma_f32_16x16x32_bf16 v[88:91], v[162:165], v[214:217], v[88:91]
	v_mfma_f32_16x16x32_bf16 v[76:79], v[146:149], v[222:225], v[76:79]
	v_mfma_f32_16x16x32_bf16 v[72:75], v[162:165], v[222:225], v[72:75]
	v_mfma_f32_16x16x32_bf16 v[126:129], v[150:153], v[202:205], v[126:129]
	v_mfma_f32_16x16x32_bf16 v[122:125], v[166:169], v[202:205], v[122:125]
	v_mfma_f32_16x16x32_bf16 v[110:113], v[150:153], v[210:213], v[110:113]
	v_mfma_f32_16x16x32_bf16 v[106:109], v[166:169], v[210:213], v[106:109]
	v_mfma_f32_16x16x32_bf16 v[92:95], v[150:153], v[218:221], v[92:95]
	v_mfma_f32_16x16x32_bf16 v[88:91], v[166:169], v[218:221], v[88:91]
	v_mfma_f32_16x16x32_bf16 v[76:79], v[150:153], v[226:229], v[76:79]
	v_mfma_f32_16x16x32_bf16 v[72:75], v[166:169], v[226:229], v[72:75]
	s_setprio 0
	s_setprio 1
	v_mfma_f32_16x16x32_bf16 v[118:121], v[170:173], v[198:201], v[118:121]
	v_mfma_f32_16x16x32_bf16 v[114:117], v[190:193], v[198:201], v[114:117]
	v_mfma_f32_16x16x32_bf16 v[102:105], v[170:173], v[206:209], v[102:105]
	v_mfma_f32_16x16x32_bf16 v[98:101], v[190:193], v[206:209], v[98:101]
	v_mfma_f32_16x16x32_bf16 v[84:87], v[170:173], v[214:217], v[84:87]
	v_mfma_f32_16x16x32_bf16 v[80:83], v[190:193], v[214:217], v[80:83]
	v_mfma_f32_16x16x32_bf16 v[68:71], v[170:173], v[222:225], v[68:71]
	v_mfma_f32_16x16x32_bf16 v[64:67], v[190:193], v[222:225], v[64:67]
	v_mfma_f32_16x16x32_bf16 v[118:121], v[186:189], v[202:205], v[118:121]
	v_mfma_f32_16x16x32_bf16 v[114:117], v[194:197], v[202:205], v[114:117]
	v_mfma_f32_16x16x32_bf16 v[102:105], v[186:189], v[210:213], v[102:105]
	v_mfma_f32_16x16x32_bf16 v[98:101], v[194:197], v[210:213], v[98:101]
	v_mfma_f32_16x16x32_bf16 v[84:87], v[186:189], v[218:221], v[84:87]
	v_mfma_f32_16x16x32_bf16 v[80:83], v[194:197], v[218:221], v[80:83]
	v_mfma_f32_16x16x32_bf16 v[68:71], v[186:189], v[226:229], v[68:71]
	v_mfma_f32_16x16x32_bf16 v[64:67], v[194:197], v[226:229], v[64:67]
	s_setprio 0
	s_barrier
	s_setprio 3
	s_add_i32 s28, s54, s36
	v_lshl_add_u64 v[154:155], v[154:155], 0, s[16:17]
	s_mov_b32 m0, s28
	ds_read_b128 v[198:201], v145 offset:49152
	ds_read_b128 v[202:205], v145 offset:50176
	ds_read_b128 v[206:209], v145 offset:51200
	ds_read_b128 v[210:213], v145 offset:52224
	ds_read_b128 v[214:217], v145 offset:53248
	ds_read_b128 v[218:221], v145 offset:54272
	ds_read_b128 v[222:225], v145 offset:55296
	ds_read_b128 v[226:229], v145 offset:56320
	global_load_lds_dwordx4 v[154:155], off
	s_add_i32 m0, s28, 0x2000
	s_add_u32 s26, s26, 0x40080
	v_lshl_add_u64 v[154:155], v[156:157], 0, s[16:17]
	s_addc_u32 s27, s27, 0
	s_add_i32 s28, s55, s36
	global_load_lds_dwordx4 v[154:155], off
	v_lshl_add_u64 v[154:155], s[26:27], 0, v[96:97]
	s_mov_b32 m0, s28
	s_nop 0
	global_load_lds_dwordx4 v[154:155], off
	v_lshl_add_u64 v[154:155], s[26:27], 0, v[130:131]
	s_add_i32 m0, s28, 0x2000
	s_nop 0
	global_load_lds_dwordx4 v[154:155], off
	v_lshl_add_u64 v[154:155], v[158:159], 0, s[16:17]
	s_mov_b32 m0, s41
	s_nop 0
	global_load_lds_dwordx4 v[154:155], off
	v_lshl_add_u64 v[154:155], v[182:183], 0, s[16:17]
	s_mov_b32 m0, s42
	s_nop 0
	global_load_lds_dwordx4 v[154:155], off
	s_setprio 0
	s_waitcnt vmcnt(8)
	s_waitcnt lgkmcnt(0)
	s_barrier
	s_setprio 1
	v_mfma_f32_16x16x32_bf16 v[60:63], v[146:149], v[198:201], v[60:63]
	v_mfma_f32_16x16x32_bf16 v[56:59], v[162:165], v[198:201], v[56:59]
	v_mfma_f32_16x16x32_bf16 v[44:47], v[146:149], v[206:209], v[44:47]
	v_mfma_f32_16x16x32_bf16 v[40:43], v[162:165], v[206:209], v[40:43]
	v_mfma_f32_16x16x32_bf16 v[28:31], v[146:149], v[214:217], v[28:31]
	v_mfma_f32_16x16x32_bf16 v[24:27], v[162:165], v[214:217], v[24:27]
	v_mfma_f32_16x16x32_bf16 v[12:15], v[146:149], v[222:225], v[12:15]
	v_mfma_f32_16x16x32_bf16 v[4:7], v[162:165], v[222:225], v[4:7]
	v_mfma_f32_16x16x32_bf16 v[60:63], v[150:153], v[202:205], v[60:63]
	v_mfma_f32_16x16x32_bf16 v[56:59], v[166:169], v[202:205], v[56:59]
	v_mfma_f32_16x16x32_bf16 v[44:47], v[150:153], v[210:213], v[44:47]
	v_mfma_f32_16x16x32_bf16 v[40:43], v[166:169], v[210:213], v[40:43]
	v_mfma_f32_16x16x32_bf16 v[28:31], v[150:153], v[218:221], v[28:31]
	v_mfma_f32_16x16x32_bf16 v[24:27], v[166:169], v[218:221], v[24:27]
	v_mfma_f32_16x16x32_bf16 v[12:15], v[150:153], v[226:229], v[12:15]
	v_mfma_f32_16x16x32_bf16 v[4:7], v[166:169], v[226:229], v[4:7]
	s_setprio 0
	s_setprio 1
	v_mfma_f32_16x16x32_bf16 v[52:55], v[170:173], v[198:201], v[52:55]
	v_mfma_f32_16x16x32_bf16 v[48:51], v[190:193], v[198:201], v[48:51]
	v_mfma_f32_16x16x32_bf16 v[36:39], v[170:173], v[206:209], v[36:39]
	v_mfma_f32_16x16x32_bf16 v[32:35], v[190:193], v[206:209], v[32:35]
	v_mfma_f32_16x16x32_bf16 v[20:23], v[170:173], v[214:217], v[20:23]
	v_mfma_f32_16x16x32_bf16 v[16:19], v[190:193], v[214:217], v[16:19]
	v_mfma_f32_16x16x32_bf16 v[8:11], v[170:173], v[222:225], v[8:11]
	v_mfma_f32_16x16x32_bf16 v[0:3], v[190:193], v[222:225], v[0:3]
	v_mfma_f32_16x16x32_bf16 v[52:55], v[186:189], v[202:205], v[52:55]
	v_mfma_f32_16x16x32_bf16 v[48:51], v[194:197], v[202:205], v[48:51]
	v_mfma_f32_16x16x32_bf16 v[36:39], v[186:189], v[210:213], v[36:39]
	v_mfma_f32_16x16x32_bf16 v[32:35], v[194:197], v[210:213], v[32:35]
	v_mfma_f32_16x16x32_bf16 v[20:23], v[186:189], v[218:221], v[20:23]
	v_mfma_f32_16x16x32_bf16 v[16:19], v[194:197], v[218:221], v[16:19]
	v_mfma_f32_16x16x32_bf16 v[8:11], v[186:189], v[226:229], v[8:11]
	v_mfma_f32_16x16x32_bf16 v[0:3], v[194:197], v[226:229], v[0:3]
	s_setprio 0
	s_barrier
	s_setprio 3
	s_add_i32 s53, s53, 2
	s_add_u32 s14, s14, 0x100
	s_addc_u32 s15, s15, 0
	s_add_u32 s51, s51, 0x100
	s_addc_u32 s52, s52, 0
	s_cmp_gt_u32 s53, 13
	s_cbranch_scc0 .LBB0_271
	s_and_b64 vcc, exec, s[12:13]
	s_cbranch_vccz .LBB0_274
	s_barrier

.LBB0_361:
	s_add_u32 s34, s30, 0xfffc0080
	s_addc_u32 s35, s31, -1
	s_add_i32 s62, 0, 0x10000
	s_cmp_eq_u32 s61, 12
	s_cselect_b32 s37, s25, s35
	s_cselect_b32 s36, s57, s34
	v_add_u32_e32 v96, s62, v151
	s_cselect_b32 s35, s15, s60
	s_cselect_b32 s34, s58, s59
	s_add_i32 s64, 0, 0x14000
	ds_read_b128 v[164:167], v96
	ds_read_b128 v[168:171], v96 offset:1024
	ds_read_b128 v[186:189], v96 offset:2048
	ds_read_b128 v[190:193], v96 offset:3072
	v_add_u32_e32 v96, s64, v151
	ds_read_b128 v[194:197], v96
	ds_read_b128 v[198:201], v96 offset:1024
	ds_read_b128 v[202:205], v96 offset:2048
	ds_read_b128 v[206:209], v96 offset:3072
	v_lshl_add_u64 v[154:155], s[30:31], 0, v[146:147]
	s_add_i32 m0, s43, 0xc000
	ds_read_b128 v[210:213], v162
	ds_read_b128 v[214:217], v162 offset:1024
	ds_read_b128 v[218:221], v162 offset:2048
	ds_read_b128 v[222:225], v162 offset:3072
	ds_read_b128 v[226:229], v162 offset:4096
	ds_read_b128 v[230:233], v162 offset:5120
	ds_read_b128 v[242:245], v162 offset:6144
	ds_read_b128 v[246:249], v162 offset:7168
	global_load_lds_dwordx4 v[154:155], off
	v_lshl_add_u64 v[154:155], s[30:31], 0, v[148:149]
	s_add_i32 m0, s43, 0xe000
	s_nop 0
	global_load_lds_dwordx4 v[154:155], off
	s_setprio 0
	s_waitcnt vmcnt(8)
	s_waitcnt lgkmcnt(0)
	s_barrier
	s_setprio 1
	v_mfma_f32_16x16x32_bf16 v[126:129], v[164:167], v[210:213], v[126:129]
	v_mfma_f32_16x16x32_bf16 v[122:125], v[186:189], v[210:213], v[122:125]
	v_mfma_f32_16x16x32_bf16 v[118:121], v[164:167], v[218:221], v[118:121]
	v_mfma_f32_16x16x32_bf16 v[114:117], v[186:189], v[218:221], v[114:117]
	v_mfma_f32_16x16x32_bf16 v[110:113], v[164:167], v[226:229], v[110:113]
	v_mfma_f32_16x16x32_bf16 v[106:109], v[186:189], v[226:229], v[106:109]
	v_mfma_f32_16x16x32_bf16 v[102:105], v[164:167], v[242:245], v[102:105]
	v_mfma_f32_16x16x32_bf16 v[98:101], v[186:189], v[242:245], v[98:101]
	v_mfma_f32_16x16x32_bf16 v[126:129], v[168:171], v[214:217], v[126:129]
	v_mfma_f32_16x16x32_bf16 v[122:125], v[190:193], v[214:217], v[122:125]
	v_mfma_f32_16x16x32_bf16 v[118:121], v[168:171], v[222:225], v[118:121]
	v_mfma_f32_16x16x32_bf16 v[114:117], v[190:193], v[222:225], v[114:117]
	v_mfma_f32_16x16x32_bf16 v[110:113], v[168:171], v[230:233], v[110:113]
	v_mfma_f32_16x16x32_bf16 v[106:109], v[190:193], v[230:233], v[106:109]
	v_mfma_f32_16x16x32_bf16 v[102:105], v[168:171], v[246:249], v[102:105]
	v_mfma_f32_16x16x32_bf16 v[98:101], v[190:193], v[246:249], v[98:101]
	s_setprio 0
	s_setprio 1
	v_mfma_f32_16x16x32_bf16 v[76:79], v[194:197], v[210:213], v[76:79]
	v_mfma_f32_16x16x32_bf16 v[64:67], v[202:205], v[210:213], v[64:67]
	v_mfma_f32_16x16x32_bf16 v[60:63], v[194:197], v[218:221], v[60:63]
	v_mfma_f32_16x16x32_bf16 v[52:55], v[202:205], v[218:221], v[52:55]
	v_mfma_f32_16x16x32_bf16 v[44:47], v[194:197], v[226:229], v[44:47]
	v_mfma_f32_16x16x32_bf16 v[40:43], v[202:205], v[226:229], v[40:43]
	v_mfma_f32_16x16x32_bf16 v[36:39], v[194:197], v[242:245], v[36:39]
	v_mfma_f32_16x16x32_bf16 v[32:35], v[202:205], v[242:245], v[32:35]
	v_mfma_f32_16x16x32_bf16 v[76:79], v[198:201], v[214:217], v[76:79]
	v_mfma_f32_16x16x32_bf16 v[64:67], v[206:209], v[214:217], v[64:67]
	v_mfma_f32_16x16x32_bf16 v[60:63], v[198:201], v[222:225], v[60:63]
	v_mfma_f32_16x16x32_bf16 v[52:55], v[206:209], v[222:225], v[52:55]
	v_mfma_f32_16x16x32_bf16 v[44:47], v[198:201], v[230:233], v[44:47]
	v_mfma_f32_16x16x32_bf16 v[40:43], v[206:209], v[230:233], v[40:43]
	v_mfma_f32_16x16x32_bf16 v[36:39], v[198:201], v[246:249], v[36:39]
	v_mfma_f32_16x16x32_bf16 v[32:35], v[206:209], v[246:249], v[32:35]
	s_setprio 0
	s_barrier
	s_setprio 3
	s_add_i32 s62, s62, s40
	v_lshl_add_u64 v[154:155], s[34:35], 0, v[134:135]
	s_mov_b32 m0, s62
	ds_read_b128 v[210:213], v162 offset:16384
	ds_read_b128 v[214:217], v162 offset:17408
	ds_read_b128 v[218:221], v162 offset:18432
	ds_read_b128 v[222:225], v162 offset:19456
	ds_read_b128 v[226:229], v162 offset:20480
	ds_read_b128 v[230:233], v162 offset:21504
	ds_read_b128 v[242:245], v162 offset:22528
	ds_read_b128 v[246:249], v162 offset:23552
	global_load_lds_dwordx4 v[154:155], off
	s_add_i32 m0, s62, 0x2000
	s_add_u32 s62, s34, 0x40000
	v_lshl_add_u64 v[156:157], s[34:35], 0, v[130:131]
	s_addc_u32 s63, s35, 0
	s_add_i32 s64, s64, s40
	global_load_lds_dwordx4 v[156:157], off
	v_lshl_add_u64 v[158:159], s[62:63], 0, v[134:135]
	s_mov_b32 m0, s64
	v_lshl_add_u64 v[172:173], s[36:37], 0, v[132:133]
	global_load_lds_dwordx4 v[158:159], off
	v_lshl_add_u64 v[158:159], s[62:63], 0, v[130:131]
	s_add_i32 m0, s64, 0x2000
	s_nop 0
	global_load_lds_dwordx4 v[158:159], off
	v_lshl_add_u64 v[158:159], s[36:37], 0, v[136:137]
	s_mov_b32 m0, s43
	s_nop 0
	global_load_lds_dwordx4 v[158:159], off
	s_mov_b32 m0, s44
	s_nop 0
	global_load_lds_dwordx4 v[172:173], off
	s_setprio 0
	s_waitcnt vmcnt(8)
	s_waitcnt lgkmcnt(0)
	s_barrier
	s_setprio 1
	v_mfma_f32_16x16x32_bf16 v[92:95], v[164:167], v[210:213], v[92:95]
	v_mfma_f32_16x16x32_bf16 v[88:91], v[186:189], v[210:213], v[88:91]
	v_mfma_f32_16x16x32_bf16 v[84:87], v[164:167], v[218:221], v[84:87]
	v_mfma_f32_16x16x32_bf16 v[80:83], v[186:189], v[218:221], v[80:83]
	v_mfma_f32_16x16x32_bf16 v[72:75], v[164:167], v[226:229], v[72:75]
	v_mfma_f32_16x16x32_bf16 v[68:71], v[186:189], v[226:229], v[68:71]
	v_mfma_f32_16x16x32_bf16 v[56:59], v[164:167], v[242:245], v[56:59]
	v_mfma_f32_16x16x32_bf16 v[48:51], v[186:189], v[242:245], v[48:51]
	v_mfma_f32_16x16x32_bf16 v[92:95], v[168:171], v[214:217], v[92:95]
	v_mfma_f32_16x16x32_bf16 v[88:91], v[190:193], v[214:217], v[88:91]
	v_mfma_f32_16x16x32_bf16 v[84:87], v[168:171], v[222:225], v[84:87]
	v_mfma_f32_16x16x32_bf16 v[80:83], v[190:193], v[222:225], v[80:83]
	v_mfma_f32_16x16x32_bf16 v[72:75], v[168:171], v[230:233], v[72:75]
	v_mfma_f32_16x16x32_bf16 v[68:71], v[190:193], v[230:233], v[68:71]
	v_mfma_f32_16x16x32_bf16 v[56:59], v[168:171], v[246:249], v[56:59]
	v_mfma_f32_16x16x32_bf16 v[48:51], v[190:193], v[246:249], v[48:51]
	s_setprio 0
	s_setprio 1
	v_mfma_f32_16x16x32_bf16 v[28:31], v[194:197], v[210:213], v[28:31]
	v_mfma_f32_16x16x32_bf16 v[24:27], v[202:205], v[210:213], v[24:27]
	v_mfma_f32_16x16x32_bf16 v[20:23], v[194:197], v[218:221], v[20:23]
	v_mfma_f32_16x16x32_bf16 v[16:19], v[202:205], v[218:221], v[16:19]
	v_mfma_f32_16x16x32_bf16 v[12:15], v[194:197], v[226:229], v[12:15]
	v_mfma_f32_16x16x32_bf16 v[8:11], v[202:205], v[226:229], v[8:11]
	v_mfma_f32_16x16x32_bf16 v[4:7], v[194:197], v[242:245], v[4:7]
	v_mfma_f32_16x16x32_bf16 v[0:3], v[202:205], v[242:245], v[0:3]
	v_mfma_f32_16x16x32_bf16 v[28:31], v[198:201], v[214:217], v[28:31]
	v_mfma_f32_16x16x32_bf16 v[24:27], v[206:209], v[214:217], v[24:27]
	v_mfma_f32_16x16x32_bf16 v[20:23], v[198:201], v[222:225], v[20:23]
	v_mfma_f32_16x16x32_bf16 v[16:19], v[206:209], v[222:225], v[16:19]
	v_mfma_f32_16x16x32_bf16 v[12:15], v[198:201], v[230:233], v[12:15]
	v_mfma_f32_16x16x32_bf16 v[8:11], v[206:209], v[230:233], v[8:11]
	v_mfma_f32_16x16x32_bf16 v[4:7], v[198:201], v[246:249], v[4:7]
	v_mfma_f32_16x16x32_bf16 v[0:3], v[206:209], v[246:249], v[0:3]
	s_setprio 0
	s_barrier
	s_setprio 3
	s_add_i32 s62, 0, 0x18000
	v_add_u32_e32 v96, s62, v151
	s_add_i32 s63, 0, 0x1c000
	ds_read_b128 v[164:167], v96
	ds_read_b128 v[168:171], v96 offset:1024
	ds_read_b128 v[186:189], v96 offset:2048
	ds_read_b128 v[190:193], v96 offset:3072
	v_add_u32_e32 v96, s63, v151
	ds_read_b128 v[194:197], v96
	ds_read_b128 v[198:201], v96 offset:1024
	ds_read_b128 v[202:205], v96 offset:2048
	ds_read_b128 v[206:209], v96 offset:3072
	s_add_u32 s36, s36, 0x40000
	s_addc_u32 s37, s37, 0
	s_mov_b32 m0, s45
	v_lshl_add_u64 v[182:183], s[36:37], 0, v[136:137]
	ds_read_b128 v[210:213], v162 offset:32768
	ds_read_b128 v[214:217], v162 offset:33792
	ds_read_b128 v[218:221], v162 offset:34816
	ds_read_b128 v[222:225], v162 offset:35840
	ds_read_b128 v[226:229], v162 offset:36864
	ds_read_b128 v[230:233], v162 offset:37888
	ds_read_b128 v[242:245], v162 offset:38912
	ds_read_b128 v[246:249], v162 offset:39936
	global_load_lds_dwordx4 v[182:183], off
	v_lshl_add_u64 v[182:183], s[36:37], 0, v[132:133]
	s_mov_b32 m0, s46
	s_nop 0
	global_load_lds_dwordx4 v[182:183], off
	s_setprio 0
	s_waitcnt vmcnt(8)
	s_waitcnt lgkmcnt(0)
	s_barrier
	s_setprio 1
	v_mfma_f32_16x16x32_bf16 v[126:129], v[164:167], v[210:213], v[126:129]
	v_mfma_f32_16x16x32_bf16 v[122:125], v[186:189], v[210:213], v[122:125]
	v_mfma_f32_16x16x32_bf16 v[118:121], v[164:167], v[218:221], v[118:121]
	v_mfma_f32_16x16x32_bf16 v[114:117], v[186:189], v[218:221], v[114:117]
	v_mfma_f32_16x16x32_bf16 v[110:113], v[164:167], v[226:229], v[110:113]
	v_mfma_f32_16x16x32_bf16 v[106:109], v[186:189], v[226:229], v[106:109]
	v_mfma_f32_16x16x32_bf16 v[102:105], v[164:167], v[242:245], v[102:105]
	v_mfma_f32_16x16x32_bf16 v[98:101], v[186:189], v[242:245], v[98:101]
	v_mfma_f32_16x16x32_bf16 v[126:129], v[168:171], v[214:217], v[126:129]
	v_mfma_f32_16x16x32_bf16 v[122:125], v[190:193], v[214:217], v[122:125]
	v_mfma_f32_16x16x32_bf16 v[118:121], v[168:171], v[222:225], v[118:121]
	v_mfma_f32_16x16x32_bf16 v[114:117], v[190:193], v[222:225], v[114:117]
	v_mfma_f32_16x16x32_bf16 v[110:113], v[168:171], v[230:233], v[110:113]
	v_mfma_f32_16x16x32_bf16 v[106:109], v[190:193], v[230:233], v[106:109]
	v_mfma_f32_16x16x32_bf16 v[102:105], v[168:171], v[246:249], v[102:105]
	v_mfma_f32_16x16x32_bf16 v[98:101], v[190:193], v[246:249], v[98:101]
	s_setprio 0
	s_setprio 1
	v_mfma_f32_16x16x32_bf16 v[76:79], v[194:197], v[210:213], v[76:79]
	v_mfma_f32_16x16x32_bf16 v[64:67], v[202:205], v[210:213], v[64:67]
	v_mfma_f32_16x16x32_bf16 v[60:63], v[194:197], v[218:221], v[60:63]
	v_mfma_f32_16x16x32_bf16 v[52:55], v[202:205], v[218:221], v[52:55]
	v_mfma_f32_16x16x32_bf16 v[44:47], v[194:197], v[226:229], v[44:47]
	v_mfma_f32_16x16x32_bf16 v[40:43], v[202:205], v[226:229], v[40:43]
	v_mfma_f32_16x16x32_bf16 v[36:39], v[194:197], v[242:245], v[36:39]
	v_mfma_f32_16x16x32_bf16 v[32:35], v[202:205], v[242:245], v[32:35]
	v_mfma_f32_16x16x32_bf16 v[76:79], v[198:201], v[214:217], v[76:79]
	v_mfma_f32_16x16x32_bf16 v[64:67], v[206:209], v[214:217], v[64:67]
	v_mfma_f32_16x16x32_bf16 v[60:63], v[198:201], v[222:225], v[60:63]
	v_mfma_f32_16x16x32_bf16 v[52:55], v[206:209], v[222:225], v[52:55]
	v_mfma_f32_16x16x32_bf16 v[44:47], v[198:201], v[230:233], v[44:47]
	v_mfma_f32_16x16x32_bf16 v[40:43], v[206:209], v[230:233], v[40:43]
	v_mfma_f32_16x16x32_bf16 v[36:39], v[198:201], v[246:249], v[36:39]
	v_mfma_f32_16x16x32_bf16 v[32:35], v[206:209], v[246:249], v[32:35]
	s_setprio 0
	s_barrier
	s_setprio 3
	s_add_i32 s36, s62, s40
	v_lshl_add_u64 v[154:155], v[154:155], 0, s[16:17]
	s_mov_b32 m0, s36
	ds_read_b128 v[210:213], v162 offset:49152
	ds_read_b128 v[214:217], v162 offset:50176
	ds_read_b128 v[218:221], v162 offset:51200
	ds_read_b128 v[222:225], v162 offset:52224
	ds_read_b128 v[226:229], v162 offset:53248
	ds_read_b128 v[230:233], v162 offset:54272
	ds_read_b128 v[242:245], v162 offset:55296
	ds_read_b128 v[246:249], v162 offset:56320
	global_load_lds_dwordx4 v[154:155], off
	s_add_i32 m0, s36, 0x2000
	s_add_u32 s34, s34, 0x40080
	v_lshl_add_u64 v[154:155], v[156:157], 0, s[16:17]
	s_addc_u32 s35, s35, 0
	s_add_i32 s36, s63, s40
	global_load_lds_dwordx4 v[154:155], off
	v_lshl_add_u64 v[154:155], s[34:35], 0, v[134:135]
	s_mov_b32 m0, s36
	s_nop 0
	global_load_lds_dwordx4 v[154:155], off
	v_lshl_add_u64 v[154:155], s[34:35], 0, v[130:131]
	s_add_i32 m0, s36, 0x2000
	s_nop 0
	global_load_lds_dwordx4 v[154:155], off
	v_lshl_add_u64 v[154:155], v[158:159], 0, s[16:17]
	s_mov_b32 m0, s50
	s_nop 0
	global_load_lds_dwordx4 v[154:155], off
	v_lshl_add_u64 v[154:155], v[172:173], 0, s[16:17]
	s_mov_b32 m0, s51
	s_nop 0
	global_load_lds_dwordx4 v[154:155], off
	s_setprio 0
	s_waitcnt vmcnt(8)
	s_waitcnt lgkmcnt(0)
	s_barrier
	s_setprio 1
	v_mfma_f32_16x16x32_bf16 v[92:95], v[164:167], v[210:213], v[92:95]
	v_mfma_f32_16x16x32_bf16 v[88:91], v[186:189], v[210:213], v[88:91]
	v_mfma_f32_16x16x32_bf16 v[84:87], v[164:167], v[218:221], v[84:87]
	v_mfma_f32_16x16x32_bf16 v[80:83], v[186:189], v[218:221], v[80:83]
	v_mfma_f32_16x16x32_bf16 v[72:75], v[164:167], v[226:229], v[72:75]
	v_mfma_f32_16x16x32_bf16 v[68:71], v[186:189], v[226:229], v[68:71]
	v_mfma_f32_16x16x32_bf16 v[56:59], v[164:167], v[242:245], v[56:59]
	v_mfma_f32_16x16x32_bf16 v[48:51], v[186:189], v[242:245], v[48:51]
	v_mfma_f32_16x16x32_bf16 v[92:95], v[168:171], v[214:217], v[92:95]
	v_mfma_f32_16x16x32_bf16 v[88:91], v[190:193], v[214:217], v[88:91]
	v_mfma_f32_16x16x32_bf16 v[84:87], v[168:171], v[222:225], v[84:87]
	v_mfma_f32_16x16x32_bf16 v[80:83], v[190:193], v[222:225], v[80:83]
	v_mfma_f32_16x16x32_bf16 v[72:75], v[168:171], v[230:233], v[72:75]
	v_mfma_f32_16x16x32_bf16 v[68:71], v[190:193], v[230:233], v[68:71]
	v_mfma_f32_16x16x32_bf16 v[56:59], v[168:171], v[246:249], v[56:59]
	v_mfma_f32_16x16x32_bf16 v[48:51], v[190:193], v[246:249], v[48:51]
	s_setprio 0
	s_setprio 1
	v_mfma_f32_16x16x32_bf16 v[28:31], v[194:197], v[210:213], v[28:31]
	v_mfma_f32_16x16x32_bf16 v[24:27], v[202:205], v[210:213], v[24:27]
	v_mfma_f32_16x16x32_bf16 v[20:23], v[194:197], v[218:221], v[20:23]
	v_mfma_f32_16x16x32_bf16 v[16:19], v[202:205], v[218:221], v[16:19]
	v_mfma_f32_16x16x32_bf16 v[12:15], v[194:197], v[226:229], v[12:15]
	v_mfma_f32_16x16x32_bf16 v[8:11], v[202:205], v[226:229], v[8:11]
	v_mfma_f32_16x16x32_bf16 v[4:7], v[194:197], v[242:245], v[4:7]
	v_mfma_f32_16x16x32_bf16 v[0:3], v[202:205], v[242:245], v[0:3]
	v_mfma_f32_16x16x32_bf16 v[28:31], v[198:201], v[214:217], v[28:31]
	v_mfma_f32_16x16x32_bf16 v[24:27], v[206:209], v[214:217], v[24:27]
	v_mfma_f32_16x16x32_bf16 v[20:23], v[198:201], v[222:225], v[20:23]
	v_mfma_f32_16x16x32_bf16 v[16:19], v[206:209], v[222:225], v[16:19]
	v_mfma_f32_16x16x32_bf16 v[12:15], v[198:201], v[230:233], v[12:15]
	v_mfma_f32_16x16x32_bf16 v[8:11], v[206:209], v[230:233], v[8:11]
	v_mfma_f32_16x16x32_bf16 v[4:7], v[198:201], v[246:249], v[4:7]
	v_mfma_f32_16x16x32_bf16 v[0:3], v[206:209], v[246:249], v[0:3]
	s_setprio 0
	s_barrier
	s_setprio 3
	s_add_i32 s61, s61, 2
	s_add_u32 s30, s30, 0x100
	s_addc_u32 s31, s31, 0
	s_add_u32 s59, s59, 0x100
	s_addc_u32 s60, s60, 0
	s_cmp_gt_u32 s61, 13
	s_cbranch_scc0 .LBB0_361
	s_and_b64 vcc, exec, s[20:21]
	s_cbranch_vccz .LBB0_364
	s_barrier

.LBB0_393:
	s_add_u32 s26, s14, 0xfffc0080
	s_addc_u32 s27, s15, -1
	s_add_i32 s57, 0, 0x10000
	s_cmp_eq_u32 s56, 12
	s_cselect_b32 s29, s19, s27
	s_cselect_b32 s28, s52, s26
	v_add_u32_e32 v151, s57, v141
	s_cselect_b32 s27, s5, s55
	s_cselect_b32 s26, s53, s54
	s_add_i32 s60, 0, 0x14000
	ds_read_b128 v[162:165], v151
	ds_read_b128 v[166:169], v151 offset:1024
	ds_read_b128 v[170:173], v151 offset:2048
	ds_read_b128 v[186:189], v151 offset:3072
	v_add_u32_e32 v151, s60, v141
	ds_read_b128 v[190:193], v151
	ds_read_b128 v[194:197], v151 offset:1024
	ds_read_b128 v[198:201], v151 offset:2048
	ds_read_b128 v[202:205], v151 offset:3072
	v_lshl_add_u64 v[152:153], s[14:15], 0, v[146:147]
	s_add_i32 m0, s39, 0xc000
	ds_read_b128 v[206:209], v150
	ds_read_b128 v[210:213], v150 offset:1024
	ds_read_b128 v[214:217], v150 offset:2048
	ds_read_b128 v[218:221], v150 offset:3072
	ds_read_b128 v[222:225], v150 offset:4096
	ds_read_b128 v[226:229], v150 offset:5120
	ds_read_b128 v[230:233], v150 offset:6144
	ds_read_b128 v[242:245], v150 offset:7168
	global_load_lds_dwordx4 v[152:153], off
	v_lshl_add_u64 v[152:153], s[14:15], 0, v[148:149]
	s_add_i32 m0, s39, 0xe000
	s_nop 0
	global_load_lds_dwordx4 v[152:153], off
	s_setprio 0
	s_waitcnt vmcnt(8)
	s_waitcnt lgkmcnt(0)
	s_barrier
	s_setprio 1
	v_mfma_f32_16x16x32_bf16 v[126:129], v[162:165], v[206:209], v[126:129]
	v_mfma_f32_16x16x32_bf16 v[122:125], v[170:173], v[206:209], v[122:125]
	v_mfma_f32_16x16x32_bf16 v[118:121], v[162:165], v[214:217], v[118:121]
	v_mfma_f32_16x16x32_bf16 v[114:117], v[170:173], v[214:217], v[114:117]
	v_mfma_f32_16x16x32_bf16 v[110:113], v[162:165], v[222:225], v[110:113]
	v_mfma_f32_16x16x32_bf16 v[106:109], v[170:173], v[222:225], v[106:109]
	v_mfma_f32_16x16x32_bf16 v[102:105], v[162:165], v[230:233], v[102:105]
	v_mfma_f32_16x16x32_bf16 v[98:101], v[170:173], v[230:233], v[98:101]
	v_mfma_f32_16x16x32_bf16 v[126:129], v[166:169], v[210:213], v[126:129]
	v_mfma_f32_16x16x32_bf16 v[122:125], v[186:189], v[210:213], v[122:125]
	v_mfma_f32_16x16x32_bf16 v[118:121], v[166:169], v[218:221], v[118:121]
	v_mfma_f32_16x16x32_bf16 v[114:117], v[186:189], v[218:221], v[114:117]
	v_mfma_f32_16x16x32_bf16 v[110:113], v[166:169], v[226:229], v[110:113]
	v_mfma_f32_16x16x32_bf16 v[106:109], v[186:189], v[226:229], v[106:109]
	v_mfma_f32_16x16x32_bf16 v[102:105], v[166:169], v[242:245], v[102:105]
	v_mfma_f32_16x16x32_bf16 v[98:101], v[186:189], v[242:245], v[98:101]
	s_setprio 0
	s_setprio 1
	v_mfma_f32_16x16x32_bf16 v[68:71], v[190:193], v[206:209], v[68:71]
	v_mfma_f32_16x16x32_bf16 v[64:67], v[198:201], v[206:209], v[64:67]
	v_mfma_f32_16x16x32_bf16 v[52:55], v[190:193], v[214:217], v[52:55]
	v_mfma_f32_16x16x32_bf16 v[48:51], v[198:201], v[214:217], v[48:51]
	v_mfma_f32_16x16x32_bf16 v[44:47], v[190:193], v[222:225], v[44:47]
	v_mfma_f32_16x16x32_bf16 v[40:43], v[198:201], v[222:225], v[40:43]
	v_mfma_f32_16x16x32_bf16 v[36:39], v[190:193], v[230:233], v[36:39]
	v_mfma_f32_16x16x32_bf16 v[32:35], v[198:201], v[230:233], v[32:35]
	v_mfma_f32_16x16x32_bf16 v[68:71], v[194:197], v[210:213], v[68:71]
	v_mfma_f32_16x16x32_bf16 v[64:67], v[202:205], v[210:213], v[64:67]
	v_mfma_f32_16x16x32_bf16 v[52:55], v[194:197], v[218:221], v[52:55]
	v_mfma_f32_16x16x32_bf16 v[48:51], v[202:205], v[218:221], v[48:51]
	v_mfma_f32_16x16x32_bf16 v[44:47], v[194:197], v[226:229], v[44:47]
	v_mfma_f32_16x16x32_bf16 v[40:43], v[202:205], v[226:229], v[40:43]
	v_mfma_f32_16x16x32_bf16 v[36:39], v[194:197], v[242:245], v[36:39]
	v_mfma_f32_16x16x32_bf16 v[32:35], v[202:205], v[242:245], v[32:35]
	s_setprio 0
	s_barrier
	s_setprio 3
	s_add_i32 s57, s57, s36
	v_lshl_add_u64 v[152:153], s[26:27], 0, v[96:97]
	s_mov_b32 m0, s57
	ds_read_b128 v[206:209], v150 offset:16384
	ds_read_b128 v[210:213], v150 offset:17408
	ds_read_b128 v[214:217], v150 offset:18432
	ds_read_b128 v[218:221], v150 offset:19456
	ds_read_b128 v[222:225], v150 offset:20480
	ds_read_b128 v[226:229], v150 offset:21504
	ds_read_b128 v[230:233], v150 offset:22528
	ds_read_b128 v[242:245], v150 offset:23552
	global_load_lds_dwordx4 v[152:153], off
	s_add_i32 m0, s57, 0x2000
	s_add_u32 s58, s26, 0x40000
	v_lshl_add_u64 v[154:155], s[26:27], 0, v[130:131]
	s_addc_u32 s59, s27, 0
	s_add_i32 s57, s60, s36
	global_load_lds_dwordx4 v[154:155], off
	v_lshl_add_u64 v[156:157], s[58:59], 0, v[96:97]
	s_mov_b32 m0, s57
	v_lshl_add_u64 v[158:159], s[28:29], 0, v[132:133]
	global_load_lds_dwordx4 v[156:157], off
	v_lshl_add_u64 v[156:157], s[58:59], 0, v[130:131]
	s_add_i32 m0, s57, 0x2000
	s_nop 0
	global_load_lds_dwordx4 v[156:157], off
	v_lshl_add_u64 v[156:157], s[28:29], 0, v[134:135]
	s_mov_b32 m0, s39
	s_nop 0
	global_load_lds_dwordx4 v[156:157], off
	s_mov_b32 m0, s40
	s_nop 0
	global_load_lds_dwordx4 v[158:159], off
	s_setprio 0
	s_waitcnt vmcnt(8)
	s_waitcnt lgkmcnt(0)
	s_barrier
	s_setprio 1
	v_mfma_f32_16x16x32_bf16 v[92:95], v[162:165], v[206:209], v[92:95]
	v_mfma_f32_16x16x32_bf16 v[88:91], v[170:173], v[206:209], v[88:91]
	v_mfma_f32_16x16x32_bf16 v[84:87], v[162:165], v[214:217], v[84:87]
	v_mfma_f32_16x16x32_bf16 v[80:83], v[170:173], v[214:217], v[80:83]
	v_mfma_f32_16x16x32_bf16 v[76:79], v[162:165], v[222:225], v[76:79]
	v_mfma_f32_16x16x32_bf16 v[72:75], v[170:173], v[222:225], v[72:75]
	v_mfma_f32_16x16x32_bf16 v[60:63], v[162:165], v[230:233], v[60:63]
	v_mfma_f32_16x16x32_bf16 v[56:59], v[170:173], v[230:233], v[56:59]
	v_mfma_f32_16x16x32_bf16 v[92:95], v[166:169], v[210:213], v[92:95]
	v_mfma_f32_16x16x32_bf16 v[88:91], v[186:189], v[210:213], v[88:91]
	v_mfma_f32_16x16x32_bf16 v[84:87], v[166:169], v[218:221], v[84:87]
	v_mfma_f32_16x16x32_bf16 v[80:83], v[186:189], v[218:221], v[80:83]
	v_mfma_f32_16x16x32_bf16 v[76:79], v[166:169], v[226:229], v[76:79]
	v_mfma_f32_16x16x32_bf16 v[72:75], v[186:189], v[226:229], v[72:75]
	v_mfma_f32_16x16x32_bf16 v[60:63], v[166:169], v[242:245], v[60:63]
	v_mfma_f32_16x16x32_bf16 v[56:59], v[186:189], v[242:245], v[56:59]
	s_setprio 0
	s_setprio 1
	v_mfma_f32_16x16x32_bf16 v[28:31], v[190:193], v[206:209], v[28:31]
	v_mfma_f32_16x16x32_bf16 v[24:27], v[198:201], v[206:209], v[24:27]
	v_mfma_f32_16x16x32_bf16 v[20:23], v[190:193], v[214:217], v[20:23]
	v_mfma_f32_16x16x32_bf16 v[16:19], v[198:201], v[214:217], v[16:19]
	v_mfma_f32_16x16x32_bf16 v[12:15], v[190:193], v[222:225], v[12:15]
	v_mfma_f32_16x16x32_bf16 v[8:11], v[198:201], v[222:225], v[8:11]
	v_mfma_f32_16x16x32_bf16 v[4:7], v[190:193], v[230:233], v[4:7]
	v_mfma_f32_16x16x32_bf16 v[0:3], v[198:201], v[230:233], v[0:3]
	v_mfma_f32_16x16x32_bf16 v[28:31], v[194:197], v[210:213], v[28:31]
	v_mfma_f32_16x16x32_bf16 v[24:27], v[202:205], v[210:213], v[24:27]
	v_mfma_f32_16x16x32_bf16 v[20:23], v[194:197], v[218:221], v[20:23]
	v_mfma_f32_16x16x32_bf16 v[16:19], v[202:205], v[218:221], v[16:19]
	v_mfma_f32_16x16x32_bf16 v[12:15], v[194:197], v[226:229], v[12:15]
	v_mfma_f32_16x16x32_bf16 v[8:11], v[202:205], v[226:229], v[8:11]
	v_mfma_f32_16x16x32_bf16 v[4:7], v[194:197], v[242:245], v[4:7]
	v_mfma_f32_16x16x32_bf16 v[0:3], v[202:205], v[242:245], v[0:3]
	s_setprio 0
	s_barrier
	s_setprio 3
	s_add_i32 s57, 0, 0x18000
	v_add_u32_e32 v151, s57, v141
	s_add_i32 s58, 0, 0x1c000
	ds_read_b128 v[162:165], v151
	ds_read_b128 v[166:169], v151 offset:1024
	ds_read_b128 v[170:173], v151 offset:2048
	ds_read_b128 v[186:189], v151 offset:3072
	v_add_u32_e32 v151, s58, v141
	ds_read_b128 v[190:193], v151
	ds_read_b128 v[194:197], v151 offset:1024
	ds_read_b128 v[198:201], v151 offset:2048
	ds_read_b128 v[202:205], v151 offset:3072
	s_add_u32 s28, s28, 0x40000
	s_addc_u32 s29, s29, 0
	s_mov_b32 m0, s41
	v_lshl_add_u64 v[182:183], s[28:29], 0, v[134:135]
	ds_read_b128 v[206:209], v150 offset:32768
	ds_read_b128 v[210:213], v150 offset:33792
	ds_read_b128 v[214:217], v150 offset:34816
	ds_read_b128 v[218:221], v150 offset:35840
	ds_read_b128 v[222:225], v150 offset:36864
	ds_read_b128 v[226:229], v150 offset:37888
	ds_read_b128 v[230:233], v150 offset:38912
	ds_read_b128 v[242:245], v150 offset:39936
	global_load_lds_dwordx4 v[182:183], off
	v_lshl_add_u64 v[182:183], s[28:29], 0, v[132:133]
	s_mov_b32 m0, s42
	s_nop 0
	global_load_lds_dwordx4 v[182:183], off
	s_setprio 0
	s_waitcnt vmcnt(8)
	s_waitcnt lgkmcnt(0)
	s_barrier
	s_setprio 1
	v_mfma_f32_16x16x32_bf16 v[126:129], v[162:165], v[206:209], v[126:129]
	v_mfma_f32_16x16x32_bf16 v[122:125], v[170:173], v[206:209], v[122:125]
	v_mfma_f32_16x16x32_bf16 v[118:121], v[162:165], v[214:217], v[118:121]
	v_mfma_f32_16x16x32_bf16 v[114:117], v[170:173], v[214:217], v[114:117]
	v_mfma_f32_16x16x32_bf16 v[110:113], v[162:165], v[222:225], v[110:113]
	v_mfma_f32_16x16x32_bf16 v[106:109], v[170:173], v[222:225], v[106:109]
	v_mfma_f32_16x16x32_bf16 v[102:105], v[162:165], v[230:233], v[102:105]
	v_mfma_f32_16x16x32_bf16 v[98:101], v[170:173], v[230:233], v[98:101]
	v_mfma_f32_16x16x32_bf16 v[126:129], v[166:169], v[210:213], v[126:129]
	v_mfma_f32_16x16x32_bf16 v[122:125], v[186:189], v[210:213], v[122:125]
	v_mfma_f32_16x16x32_bf16 v[118:121], v[166:169], v[218:221], v[118:121]
	v_mfma_f32_16x16x32_bf16 v[114:117], v[186:189], v[218:221], v[114:117]
	v_mfma_f32_16x16x32_bf16 v[110:113], v[166:169], v[226:229], v[110:113]
	v_mfma_f32_16x16x32_bf16 v[106:109], v[186:189], v[226:229], v[106:109]
	v_mfma_f32_16x16x32_bf16 v[102:105], v[166:169], v[242:245], v[102:105]
	v_mfma_f32_16x16x32_bf16 v[98:101], v[186:189], v[242:245], v[98:101]
	s_setprio 0
	s_setprio 1
	v_mfma_f32_16x16x32_bf16 v[68:71], v[190:193], v[206:209], v[68:71]
	v_mfma_f32_16x16x32_bf16 v[64:67], v[198:201], v[206:209], v[64:67]
	v_mfma_f32_16x16x32_bf16 v[52:55], v[190:193], v[214:217], v[52:55]
	v_mfma_f32_16x16x32_bf16 v[48:51], v[198:201], v[214:217], v[48:51]
	v_mfma_f32_16x16x32_bf16 v[44:47], v[190:193], v[222:225], v[44:47]
	v_mfma_f32_16x16x32_bf16 v[40:43], v[198:201], v[222:225], v[40:43]
	v_mfma_f32_16x16x32_bf16 v[36:39], v[190:193], v[230:233], v[36:39]
	v_mfma_f32_16x16x32_bf16 v[32:35], v[198:201], v[230:233], v[32:35]
	v_mfma_f32_16x16x32_bf16 v[68:71], v[194:197], v[210:213], v[68:71]
	v_mfma_f32_16x16x32_bf16 v[64:67], v[202:205], v[210:213], v[64:67]
	v_mfma_f32_16x16x32_bf16 v[52:55], v[194:197], v[218:221], v[52:55]
	v_mfma_f32_16x16x32_bf16 v[48:51], v[202:205], v[218:221], v[48:51]
	v_mfma_f32_16x16x32_bf16 v[44:47], v[194:197], v[226:229], v[44:47]
	v_mfma_f32_16x16x32_bf16 v[40:43], v[202:205], v[226:229], v[40:43]
	v_mfma_f32_16x16x32_bf16 v[36:39], v[194:197], v[242:245], v[36:39]
	v_mfma_f32_16x16x32_bf16 v[32:35], v[202:205], v[242:245], v[32:35]
	s_setprio 0
	s_barrier
	s_setprio 3
	s_add_i32 s28, s57, s36
	v_lshl_add_u64 v[152:153], v[152:153], 0, s[16:17]
	s_mov_b32 m0, s28
	ds_read_b128 v[206:209], v150 offset:49152
	ds_read_b128 v[210:213], v150 offset:50176
	ds_read_b128 v[214:217], v150 offset:51200
	ds_read_b128 v[218:221], v150 offset:52224
	ds_read_b128 v[222:225], v150 offset:53248
	ds_read_b128 v[226:229], v150 offset:54272
	ds_read_b128 v[230:233], v150 offset:55296
	ds_read_b128 v[242:245], v150 offset:56320
	global_load_lds_dwordx4 v[152:153], off
	s_add_i32 m0, s28, 0x2000
	s_add_u32 s26, s26, 0x40080
	v_lshl_add_u64 v[152:153], v[154:155], 0, s[16:17]
	s_addc_u32 s27, s27, 0
	s_add_i32 s28, s58, s36
	global_load_lds_dwordx4 v[152:153], off
	v_lshl_add_u64 v[152:153], s[26:27], 0, v[96:97]
	s_mov_b32 m0, s28
	s_nop 0
	global_load_lds_dwordx4 v[152:153], off
	v_lshl_add_u64 v[152:153], s[26:27], 0, v[130:131]
	s_add_i32 m0, s28, 0x2000
	s_nop 0
	global_load_lds_dwordx4 v[152:153], off
	v_lshl_add_u64 v[152:153], v[156:157], 0, s[16:17]
	s_mov_b32 m0, s45
	s_nop 0
	global_load_lds_dwordx4 v[152:153], off
	v_lshl_add_u64 v[152:153], v[158:159], 0, s[16:17]
	s_mov_b32 m0, s46
	s_nop 0
	global_load_lds_dwordx4 v[152:153], off
	s_setprio 0
	s_waitcnt vmcnt(8)
	s_waitcnt lgkmcnt(0)
	s_barrier
	s_setprio 1
	v_mfma_f32_16x16x32_bf16 v[92:95], v[162:165], v[206:209], v[92:95]
	v_mfma_f32_16x16x32_bf16 v[88:91], v[170:173], v[206:209], v[88:91]
	v_mfma_f32_16x16x32_bf16 v[84:87], v[162:165], v[214:217], v[84:87]
	v_mfma_f32_16x16x32_bf16 v[80:83], v[170:173], v[214:217], v[80:83]
	v_mfma_f32_16x16x32_bf16 v[76:79], v[162:165], v[222:225], v[76:79]
	v_mfma_f32_16x16x32_bf16 v[72:75], v[170:173], v[222:225], v[72:75]
	v_mfma_f32_16x16x32_bf16 v[60:63], v[162:165], v[230:233], v[60:63]
	v_mfma_f32_16x16x32_bf16 v[56:59], v[170:173], v[230:233], v[56:59]
	v_mfma_f32_16x16x32_bf16 v[92:95], v[166:169], v[210:213], v[92:95]
	v_mfma_f32_16x16x32_bf16 v[88:91], v[186:189], v[210:213], v[88:91]
	v_mfma_f32_16x16x32_bf16 v[84:87], v[166:169], v[218:221], v[84:87]
	v_mfma_f32_16x16x32_bf16 v[80:83], v[186:189], v[218:221], v[80:83]
	v_mfma_f32_16x16x32_bf16 v[76:79], v[166:169], v[226:229], v[76:79]
	v_mfma_f32_16x16x32_bf16 v[72:75], v[186:189], v[226:229], v[72:75]
	v_mfma_f32_16x16x32_bf16 v[60:63], v[166:169], v[242:245], v[60:63]
	v_mfma_f32_16x16x32_bf16 v[56:59], v[186:189], v[242:245], v[56:59]
	s_setprio 0
	s_setprio 1
	v_mfma_f32_16x16x32_bf16 v[28:31], v[190:193], v[206:209], v[28:31]
	v_mfma_f32_16x16x32_bf16 v[24:27], v[198:201], v[206:209], v[24:27]
	v_mfma_f32_16x16x32_bf16 v[20:23], v[190:193], v[214:217], v[20:23]
	v_mfma_f32_16x16x32_bf16 v[16:19], v[198:201], v[214:217], v[16:19]
	v_mfma_f32_16x16x32_bf16 v[12:15], v[190:193], v[222:225], v[12:15]
	v_mfma_f32_16x16x32_bf16 v[8:11], v[198:201], v[222:225], v[8:11]
	v_mfma_f32_16x16x32_bf16 v[4:7], v[190:193], v[230:233], v[4:7]
	v_mfma_f32_16x16x32_bf16 v[0:3], v[198:201], v[230:233], v[0:3]
	v_mfma_f32_16x16x32_bf16 v[28:31], v[194:197], v[210:213], v[28:31]
	v_mfma_f32_16x16x32_bf16 v[24:27], v[202:205], v[210:213], v[24:27]
	v_mfma_f32_16x16x32_bf16 v[20:23], v[194:197], v[218:221], v[20:23]
	v_mfma_f32_16x16x32_bf16 v[16:19], v[202:205], v[218:221], v[16:19]
	v_mfma_f32_16x16x32_bf16 v[12:15], v[194:197], v[226:229], v[12:15]
	v_mfma_f32_16x16x32_bf16 v[8:11], v[202:205], v[226:229], v[8:11]
	v_mfma_f32_16x16x32_bf16 v[4:7], v[194:197], v[242:245], v[4:7]
	v_mfma_f32_16x16x32_bf16 v[0:3], v[202:205], v[242:245], v[0:3]
	s_setprio 0
	s_barrier
	s_setprio 3
	s_add_i32 s56, s56, 2
	s_add_u32 s14, s14, 0x100
	s_addc_u32 s15, s15, 0
	s_add_u32 s54, s54, 0x100
	s_addc_u32 s55, s55, 0
	s_cmp_gt_u32 s56, 13
	s_cbranch_scc0 .LBB0_393
	s_and_b64 vcc, exec, s[12:13]
	s_cbranch_vccz .LBB0_396
	s_barrier

.LBB0_427:
	s_add_u32 s14, s4, 0xfffc0080
	s_addc_u32 s15, s5, -1
	s_add_i32 s62, 0, 0x10000
	s_cmp_eq_u32 s61, 12
	s_cselect_b32 s37, s29, s15
	s_cselect_b32 s36, s57, s14
	v_add_u32_e32 v154, s62, v169
	s_cselect_b32 s15, s27, s60
	s_cselect_b32 s14, s58, s59
	s_add_i32 s64, 0, 0x14000
	ds_read_b128 v[142:145], v154
	ds_read_b128 v[146:149], v154 offset:1024
	ds_read_b128 v[150:153], v154 offset:2048
	ds_read_b128 v[162:165], v154 offset:3072
	v_add_u32_e32 v154, s64, v169
	ds_read_b128 v[186:189], v154
	ds_read_b128 v[190:193], v154 offset:1024
	ds_read_b128 v[194:197], v154 offset:2048
	ds_read_b128 v[198:201], v154 offset:3072
	v_lshl_add_u64 v[154:155], s[4:5], 0, v[138:139]
	s_add_i32 m0, s43, 0xc000
	ds_read_b128 v[202:205], v173
	ds_read_b128 v[206:209], v173 offset:1024
	ds_read_b128 v[210:213], v173 offset:2048
	ds_read_b128 v[214:217], v173 offset:3072
	ds_read_b128 v[218:221], v173 offset:4096
	ds_read_b128 v[222:225], v173 offset:5120
	ds_read_b128 v[226:229], v173 offset:6144
	ds_read_b128 v[230:233], v173 offset:7168
	global_load_lds_dwordx4 v[154:155], off
	v_lshl_add_u64 v[154:155], s[4:5], 0, v[140:141]
	s_add_i32 m0, s43, 0xe000
	s_nop 0
	global_load_lds_dwordx4 v[154:155], off
	s_setprio 0
	s_waitcnt vmcnt(8)
	s_waitcnt lgkmcnt(0)
	s_barrier
	s_setprio 1
	v_mfma_f32_16x16x32_bf16 v[126:129], v[142:145], v[202:205], v[126:129]
	v_mfma_f32_16x16x32_bf16 v[122:125], v[150:153], v[202:205], v[122:125]
	v_mfma_f32_16x16x32_bf16 v[110:113], v[142:145], v[210:213], v[110:113]
	v_mfma_f32_16x16x32_bf16 v[106:109], v[150:153], v[210:213], v[106:109]
	v_mfma_f32_16x16x32_bf16 v[92:95], v[142:145], v[218:221], v[92:95]
	v_mfma_f32_16x16x32_bf16 v[88:91], v[150:153], v[218:221], v[88:91]
	v_mfma_f32_16x16x32_bf16 v[76:79], v[142:145], v[226:229], v[76:79]
	v_mfma_f32_16x16x32_bf16 v[72:75], v[150:153], v[226:229], v[72:75]
	v_mfma_f32_16x16x32_bf16 v[126:129], v[146:149], v[206:209], v[126:129]
	v_mfma_f32_16x16x32_bf16 v[122:125], v[162:165], v[206:209], v[122:125]
	v_mfma_f32_16x16x32_bf16 v[110:113], v[146:149], v[214:217], v[110:113]
	v_mfma_f32_16x16x32_bf16 v[106:109], v[162:165], v[214:217], v[106:109]
	v_mfma_f32_16x16x32_bf16 v[92:95], v[146:149], v[222:225], v[92:95]
	v_mfma_f32_16x16x32_bf16 v[88:91], v[162:165], v[222:225], v[88:91]
	v_mfma_f32_16x16x32_bf16 v[76:79], v[146:149], v[230:233], v[76:79]
	v_mfma_f32_16x16x32_bf16 v[72:75], v[162:165], v[230:233], v[72:75]
	s_setprio 0
	s_setprio 1
	v_mfma_f32_16x16x32_bf16 v[118:121], v[186:189], v[202:205], v[118:121]
	v_mfma_f32_16x16x32_bf16 v[114:117], v[194:197], v[202:205], v[114:117]
	v_mfma_f32_16x16x32_bf16 v[102:105], v[186:189], v[210:213], v[102:105]
	v_mfma_f32_16x16x32_bf16 v[98:101], v[194:197], v[210:213], v[98:101]
	v_mfma_f32_16x16x32_bf16 v[84:87], v[186:189], v[218:221], v[84:87]
	v_mfma_f32_16x16x32_bf16 v[80:83], v[194:197], v[218:221], v[80:83]
	v_mfma_f32_16x16x32_bf16 v[68:71], v[186:189], v[226:229], v[68:71]
	v_mfma_f32_16x16x32_bf16 v[64:67], v[194:197], v[226:229], v[64:67]
	v_mfma_f32_16x16x32_bf16 v[118:121], v[190:193], v[206:209], v[118:121]
	v_mfma_f32_16x16x32_bf16 v[114:117], v[198:201], v[206:209], v[114:117]
	v_mfma_f32_16x16x32_bf16 v[102:105], v[190:193], v[214:217], v[102:105]
	v_mfma_f32_16x16x32_bf16 v[98:101], v[198:201], v[214:217], v[98:101]
	v_mfma_f32_16x16x32_bf16 v[84:87], v[190:193], v[222:225], v[84:87]
	v_mfma_f32_16x16x32_bf16 v[80:83], v[198:201], v[222:225], v[80:83]
	v_mfma_f32_16x16x32_bf16 v[68:71], v[190:193], v[230:233], v[68:71]
	v_mfma_f32_16x16x32_bf16 v[64:67], v[198:201], v[230:233], v[64:67]
	s_setprio 0
	s_barrier
	s_setprio 3
	s_add_i32 s62, s62, s42
	v_lshl_add_u64 v[154:155], s[14:15], 0, v[96:97]
	s_mov_b32 m0, s62
	ds_read_b128 v[202:205], v173 offset:16384
	ds_read_b128 v[206:209], v173 offset:17408
	ds_read_b128 v[210:213], v173 offset:18432
	ds_read_b128 v[214:217], v173 offset:19456
	ds_read_b128 v[218:221], v173 offset:20480
	ds_read_b128 v[222:225], v173 offset:21504
	ds_read_b128 v[226:229], v173 offset:22528
	ds_read_b128 v[230:233], v173 offset:23552
	global_load_lds_dwordx4 v[154:155], off
	s_add_i32 m0, s62, 0x2000
	s_add_u32 s62, s14, 0x40000
	v_lshl_add_u64 v[156:157], s[14:15], 0, v[130:131]
	s_addc_u32 s63, s15, 0
	s_add_i32 s64, s64, s42
	global_load_lds_dwordx4 v[156:157], off
	v_lshl_add_u64 v[158:159], s[62:63], 0, v[96:97]
	s_mov_b32 m0, s64
	v_lshl_add_u64 v[166:167], s[36:37], 0, v[132:133]
	global_load_lds_dwordx4 v[158:159], off
	v_lshl_add_u64 v[158:159], s[62:63], 0, v[130:131]
	s_add_i32 m0, s64, 0x2000
	s_nop 0
	global_load_lds_dwordx4 v[158:159], off
	v_lshl_add_u64 v[158:159], s[36:37], 0, v[134:135]
	s_mov_b32 m0, s43
	s_nop 0
	global_load_lds_dwordx4 v[158:159], off
	s_mov_b32 m0, s44
	s_nop 0
	global_load_lds_dwordx4 v[166:167], off
	s_setprio 0
	s_waitcnt vmcnt(8)
	s_waitcnt lgkmcnt(0)
	s_barrier
	s_setprio 1
	v_mfma_f32_16x16x32_bf16 v[60:63], v[142:145], v[202:205], v[60:63]
	v_mfma_f32_16x16x32_bf16 v[56:59], v[150:153], v[202:205], v[56:59]
	v_mfma_f32_16x16x32_bf16 v[44:47], v[142:145], v[210:213], v[44:47]
	v_mfma_f32_16x16x32_bf16 v[40:43], v[150:153], v[210:213], v[40:43]
	v_mfma_f32_16x16x32_bf16 v[28:31], v[142:145], v[218:221], v[28:31]
	v_mfma_f32_16x16x32_bf16 v[24:27], v[150:153], v[218:221], v[24:27]
	v_mfma_f32_16x16x32_bf16 v[12:15], v[142:145], v[226:229], v[12:15]
	v_mfma_f32_16x16x32_bf16 v[8:11], v[150:153], v[226:229], v[8:11]
	v_mfma_f32_16x16x32_bf16 v[60:63], v[146:149], v[206:209], v[60:63]
	v_mfma_f32_16x16x32_bf16 v[56:59], v[162:165], v[206:209], v[56:59]
	v_mfma_f32_16x16x32_bf16 v[44:47], v[146:149], v[214:217], v[44:47]
	v_mfma_f32_16x16x32_bf16 v[40:43], v[162:165], v[214:217], v[40:43]
	v_mfma_f32_16x16x32_bf16 v[28:31], v[146:149], v[222:225], v[28:31]
	v_mfma_f32_16x16x32_bf16 v[24:27], v[162:165], v[222:225], v[24:27]
	v_mfma_f32_16x16x32_bf16 v[12:15], v[146:149], v[230:233], v[12:15]
	v_mfma_f32_16x16x32_bf16 v[8:11], v[162:165], v[230:233], v[8:11]
	s_setprio 0
	s_setprio 1
	v_mfma_f32_16x16x32_bf16 v[52:55], v[186:189], v[202:205], v[52:55]
	v_mfma_f32_16x16x32_bf16 v[48:51], v[194:197], v[202:205], v[48:51]
	v_mfma_f32_16x16x32_bf16 v[36:39], v[186:189], v[210:213], v[36:39]
	v_mfma_f32_16x16x32_bf16 v[32:35], v[194:197], v[210:213], v[32:35]
	v_mfma_f32_16x16x32_bf16 v[20:23], v[186:189], v[218:221], v[20:23]
	v_mfma_f32_16x16x32_bf16 v[16:19], v[194:197], v[218:221], v[16:19]
	v_mfma_f32_16x16x32_bf16 v[4:7], v[186:189], v[226:229], v[4:7]
	v_mfma_f32_16x16x32_bf16 v[0:3], v[194:197], v[226:229], v[0:3]
	v_mfma_f32_16x16x32_bf16 v[52:55], v[190:193], v[206:209], v[52:55]
	v_mfma_f32_16x16x32_bf16 v[48:51], v[198:201], v[206:209], v[48:51]
	v_mfma_f32_16x16x32_bf16 v[36:39], v[190:193], v[214:217], v[36:39]
	v_mfma_f32_16x16x32_bf16 v[32:35], v[198:201], v[214:217], v[32:35]
	v_mfma_f32_16x16x32_bf16 v[20:23], v[190:193], v[222:225], v[20:23]
	v_mfma_f32_16x16x32_bf16 v[16:19], v[198:201], v[222:225], v[16:19]
	v_mfma_f32_16x16x32_bf16 v[4:7], v[190:193], v[230:233], v[4:7]
	v_mfma_f32_16x16x32_bf16 v[0:3], v[198:201], v[230:233], v[0:3]
	s_setprio 0
	s_barrier
	s_setprio 3
	s_add_i32 s62, 0, 0x18000
	s_add_i32 s63, 0, 0x1c000
	v_add_u32_e32 v162, s62, v169
	v_add_u32_e32 v182, s63, v169
	ds_read_b128 v[142:145], v162
	ds_read_b128 v[146:149], v162 offset:1024
	ds_read_b128 v[150:153], v162 offset:2048
	ds_read_b128 v[162:165], v162 offset:3072
	ds_read_b128 v[186:189], v182
	ds_read_b128 v[190:193], v182 offset:1024
	ds_read_b128 v[194:197], v182 offset:2048
	ds_read_b128 v[198:201], v182 offset:3072
	s_add_u32 s36, s36, 0x40000
	s_addc_u32 s37, s37, 0
	s_mov_b32 m0, s45
	v_lshl_add_u64 v[182:183], s[36:37], 0, v[134:135]
	ds_read_b128 v[202:205], v173 offset:32768
	ds_read_b128 v[206:209], v173 offset:33792
	ds_read_b128 v[210:213], v173 offset:34816
	ds_read_b128 v[214:217], v173 offset:35840
	ds_read_b128 v[218:221], v173 offset:36864
	ds_read_b128 v[222:225], v173 offset:37888
	ds_read_b128 v[226:229], v173 offset:38912
	ds_read_b128 v[230:233], v173 offset:39936
	global_load_lds_dwordx4 v[182:183], off
	v_lshl_add_u64 v[182:183], s[36:37], 0, v[132:133]
	s_mov_b32 m0, s46
	s_nop 0
	global_load_lds_dwordx4 v[182:183], off
	s_setprio 0
	s_waitcnt vmcnt(8)
	s_waitcnt lgkmcnt(0)
	s_barrier
	s_setprio 1
	v_mfma_f32_16x16x32_bf16 v[126:129], v[142:145], v[202:205], v[126:129]
	v_mfma_f32_16x16x32_bf16 v[122:125], v[150:153], v[202:205], v[122:125]
	v_mfma_f32_16x16x32_bf16 v[110:113], v[142:145], v[210:213], v[110:113]
	v_mfma_f32_16x16x32_bf16 v[106:109], v[150:153], v[210:213], v[106:109]
	v_mfma_f32_16x16x32_bf16 v[92:95], v[142:145], v[218:221], v[92:95]
	v_mfma_f32_16x16x32_bf16 v[88:91], v[150:153], v[218:221], v[88:91]
	v_mfma_f32_16x16x32_bf16 v[76:79], v[142:145], v[226:229], v[76:79]
	v_mfma_f32_16x16x32_bf16 v[72:75], v[150:153], v[226:229], v[72:75]
	v_mfma_f32_16x16x32_bf16 v[126:129], v[146:149], v[206:209], v[126:129]
	v_mfma_f32_16x16x32_bf16 v[122:125], v[162:165], v[206:209], v[122:125]
	v_mfma_f32_16x16x32_bf16 v[110:113], v[146:149], v[214:217], v[110:113]
	v_mfma_f32_16x16x32_bf16 v[106:109], v[162:165], v[214:217], v[106:109]
	v_mfma_f32_16x16x32_bf16 v[92:95], v[146:149], v[222:225], v[92:95]
	v_mfma_f32_16x16x32_bf16 v[88:91], v[162:165], v[222:225], v[88:91]
	v_mfma_f32_16x16x32_bf16 v[76:79], v[146:149], v[230:233], v[76:79]
	v_mfma_f32_16x16x32_bf16 v[72:75], v[162:165], v[230:233], v[72:75]
	s_setprio 0
	s_setprio 1
	v_mfma_f32_16x16x32_bf16 v[118:121], v[186:189], v[202:205], v[118:121]
	v_mfma_f32_16x16x32_bf16 v[114:117], v[194:197], v[202:205], v[114:117]
	v_mfma_f32_16x16x32_bf16 v[102:105], v[186:189], v[210:213], v[102:105]
	v_mfma_f32_16x16x32_bf16 v[98:101], v[194:197], v[210:213], v[98:101]
	v_mfma_f32_16x16x32_bf16 v[84:87], v[186:189], v[218:221], v[84:87]
	v_mfma_f32_16x16x32_bf16 v[80:83], v[194:197], v[218:221], v[80:83]
	v_mfma_f32_16x16x32_bf16 v[68:71], v[186:189], v[226:229], v[68:71]
	v_mfma_f32_16x16x32_bf16 v[64:67], v[194:197], v[226:229], v[64:67]
	v_mfma_f32_16x16x32_bf16 v[118:121], v[190:193], v[206:209], v[118:121]
	v_mfma_f32_16x16x32_bf16 v[114:117], v[198:201], v[206:209], v[114:117]
	v_mfma_f32_16x16x32_bf16 v[102:105], v[190:193], v[214:217], v[102:105]
	v_mfma_f32_16x16x32_bf16 v[98:101], v[198:201], v[214:217], v[98:101]
	v_mfma_f32_16x16x32_bf16 v[84:87], v[190:193], v[222:225], v[84:87]
	v_mfma_f32_16x16x32_bf16 v[80:83], v[198:201], v[222:225], v[80:83]
	v_mfma_f32_16x16x32_bf16 v[68:71], v[190:193], v[230:233], v[68:71]
	v_mfma_f32_16x16x32_bf16 v[64:67], v[198:201], v[230:233], v[64:67]
	s_setprio 0
	s_barrier
	s_setprio 3
	s_add_i32 s36, s62, s42
	v_lshl_add_u64 v[154:155], v[154:155], 0, s[16:17]
	s_mov_b32 m0, s36
	ds_read_b128 v[202:205], v173 offset:49152
	ds_read_b128 v[206:209], v173 offset:50176
	ds_read_b128 v[210:213], v173 offset:51200
	ds_read_b128 v[214:217], v173 offset:52224
	ds_read_b128 v[218:221], v173 offset:53248
	ds_read_b128 v[222:225], v173 offset:54272
	ds_read_b128 v[226:229], v173 offset:55296
	ds_read_b128 v[230:233], v173 offset:56320
	global_load_lds_dwordx4 v[154:155], off
	s_add_i32 m0, s36, 0x2000
	s_add_u32 s14, s14, 0x40080
	v_lshl_add_u64 v[154:155], v[156:157], 0, s[16:17]
	s_addc_u32 s15, s15, 0
	s_add_i32 s36, s63, s42
	global_load_lds_dwordx4 v[154:155], off
	v_lshl_add_u64 v[154:155], s[14:15], 0, v[96:97]
	s_mov_b32 m0, s36
	s_nop 0
	global_load_lds_dwordx4 v[154:155], off
	v_lshl_add_u64 v[154:155], s[14:15], 0, v[130:131]
	s_add_i32 m0, s36, 0x2000
	s_nop 0
	global_load_lds_dwordx4 v[154:155], off
	v_lshl_add_u64 v[154:155], v[158:159], 0, s[16:17]
	s_mov_b32 m0, s52
	s_nop 0
	global_load_lds_dwordx4 v[154:155], off
	v_lshl_add_u64 v[154:155], v[166:167], 0, s[16:17]
	s_mov_b32 m0, s53
	s_nop 0
	global_load_lds_dwordx4 v[154:155], off
	s_setprio 0
	s_waitcnt vmcnt(8)
	s_waitcnt lgkmcnt(0)
	s_barrier
	s_setprio 1
	v_mfma_f32_16x16x32_bf16 v[60:63], v[142:145], v[202:205], v[60:63]
	v_mfma_f32_16x16x32_bf16 v[56:59], v[150:153], v[202:205], v[56:59]
	v_mfma_f32_16x16x32_bf16 v[44:47], v[142:145], v[210:213], v[44:47]
	v_mfma_f32_16x16x32_bf16 v[40:43], v[150:153], v[210:213], v[40:43]
	v_mfma_f32_16x16x32_bf16 v[28:31], v[142:145], v[218:221], v[28:31]
	v_mfma_f32_16x16x32_bf16 v[24:27], v[150:153], v[218:221], v[24:27]
	v_mfma_f32_16x16x32_bf16 v[12:15], v[142:145], v[226:229], v[12:15]
	v_mfma_f32_16x16x32_bf16 v[8:11], v[150:153], v[226:229], v[8:11]
	v_mfma_f32_16x16x32_bf16 v[60:63], v[146:149], v[206:209], v[60:63]
	v_mfma_f32_16x16x32_bf16 v[56:59], v[162:165], v[206:209], v[56:59]
	v_mfma_f32_16x16x32_bf16 v[44:47], v[146:149], v[214:217], v[44:47]
	v_mfma_f32_16x16x32_bf16 v[40:43], v[162:165], v[214:217], v[40:43]
	v_mfma_f32_16x16x32_bf16 v[28:31], v[146:149], v[222:225], v[28:31]
	v_mfma_f32_16x16x32_bf16 v[24:27], v[162:165], v[222:225], v[24:27]
	v_mfma_f32_16x16x32_bf16 v[12:15], v[146:149], v[230:233], v[12:15]
	v_mfma_f32_16x16x32_bf16 v[8:11], v[162:165], v[230:233], v[8:11]
	s_setprio 0
	s_setprio 1
	v_mfma_f32_16x16x32_bf16 v[52:55], v[186:189], v[202:205], v[52:55]
	v_mfma_f32_16x16x32_bf16 v[48:51], v[194:197], v[202:205], v[48:51]
	v_mfma_f32_16x16x32_bf16 v[36:39], v[186:189], v[210:213], v[36:39]
	v_mfma_f32_16x16x32_bf16 v[32:35], v[194:197], v[210:213], v[32:35]
	v_mfma_f32_16x16x32_bf16 v[20:23], v[186:189], v[218:221], v[20:23]
	v_mfma_f32_16x16x32_bf16 v[16:19], v[194:197], v[218:221], v[16:19]
	v_mfma_f32_16x16x32_bf16 v[4:7], v[186:189], v[226:229], v[4:7]
	v_mfma_f32_16x16x32_bf16 v[0:3], v[194:197], v[226:229], v[0:3]
	v_mfma_f32_16x16x32_bf16 v[52:55], v[190:193], v[206:209], v[52:55]
	v_mfma_f32_16x16x32_bf16 v[48:51], v[198:201], v[206:209], v[48:51]
	v_mfma_f32_16x16x32_bf16 v[36:39], v[190:193], v[214:217], v[36:39]
	v_mfma_f32_16x16x32_bf16 v[32:35], v[198:201], v[214:217], v[32:35]
	v_mfma_f32_16x16x32_bf16 v[20:23], v[190:193], v[222:225], v[20:23]
	v_mfma_f32_16x16x32_bf16 v[16:19], v[198:201], v[222:225], v[16:19]
	v_mfma_f32_16x16x32_bf16 v[4:7], v[190:193], v[230:233], v[4:7]
	v_mfma_f32_16x16x32_bf16 v[0:3], v[198:201], v[230:233], v[0:3]
	s_setprio 0
	s_barrier
	s_setprio 3
	s_add_i32 s61, s61, 2
	s_add_u32 s4, s4, 0x100
	s_addc_u32 s5, s5, 0
	s_add_u32 s59, s59, 0x100
	s_addc_u32 s60, s60, 0
	s_cmp_gt_u32 s61, 13
	s_cbranch_scc0 .LBB0_427
	s_and_b64 vcc, exec, s[24:25]
	s_cbranch_vccz .LBB0_430
	s_barrier

.LBB0_449:
	s_add_u32 s30, s14, 0xfffc0080
	s_addc_u32 s31, s15, -1
	s_add_i32 s60, 0, 0x10000
	s_cmp_eq_u32 s59, 12
	s_cselect_b32 s35, s25, s31
	s_cselect_b32 s34, s55, s30
	v_add_u32_e32 v96, s60, v151
	s_cselect_b32 s31, s13, s58
	s_cselect_b32 s30, s56, s57
	s_add_i32 s62, 0, 0x14000
	ds_read_b128 v[144:147], v96
	ds_read_b128 v[164:167], v96 offset:1024
	ds_read_b128 v[168:171], v96 offset:2048
	ds_read_b128 v[186:189], v96 offset:3072
	v_add_u32_e32 v96, s62, v151
	ds_read_b128 v[190:193], v96
	ds_read_b128 v[194:197], v96 offset:1024
	ds_read_b128 v[198:201], v96 offset:2048
	ds_read_b128 v[202:205], v96 offset:3072
	v_lshl_add_u64 v[148:149], s[14:15], 0, v[140:141]
	s_add_i32 m0, s41, 0xc000
	ds_read_b128 v[206:209], v163
	ds_read_b128 v[210:213], v163 offset:1024
	ds_read_b128 v[214:217], v163 offset:2048
	ds_read_b128 v[218:221], v163 offset:3072
	ds_read_b128 v[222:225], v163 offset:4096
	ds_read_b128 v[226:229], v163 offset:5120
	ds_read_b128 v[230:233], v163 offset:6144
	ds_read_b128 v[242:245], v163 offset:7168
	global_load_lds_dwordx4 v[148:149], off
	v_lshl_add_u64 v[148:149], s[14:15], 0, v[142:143]
	s_add_i32 m0, s41, 0xe000
	s_nop 0
	global_load_lds_dwordx4 v[148:149], off
	s_setprio 0
	s_waitcnt vmcnt(8)
	s_waitcnt lgkmcnt(0)
	s_barrier
	s_setprio 1
	v_mfma_f32_16x16x32_bf16 v[126:129], v[144:147], v[206:209], v[126:129]
	v_mfma_f32_16x16x32_bf16 v[122:125], v[168:171], v[206:209], v[122:125]
	v_mfma_f32_16x16x32_bf16 v[110:113], v[144:147], v[214:217], v[110:113]
	v_mfma_f32_16x16x32_bf16 v[106:109], v[168:171], v[214:217], v[106:109]
	v_mfma_f32_16x16x32_bf16 v[92:95], v[144:147], v[222:225], v[92:95]
	v_mfma_f32_16x16x32_bf16 v[88:91], v[168:171], v[222:225], v[88:91]
	v_mfma_f32_16x16x32_bf16 v[76:79], v[144:147], v[230:233], v[76:79]
	v_mfma_f32_16x16x32_bf16 v[72:75], v[168:171], v[230:233], v[72:75]
	v_mfma_f32_16x16x32_bf16 v[126:129], v[164:167], v[210:213], v[126:129]
	v_mfma_f32_16x16x32_bf16 v[122:125], v[186:189], v[210:213], v[122:125]
	v_mfma_f32_16x16x32_bf16 v[110:113], v[164:167], v[218:221], v[110:113]
	v_mfma_f32_16x16x32_bf16 v[106:109], v[186:189], v[218:221], v[106:109]
	v_mfma_f32_16x16x32_bf16 v[92:95], v[164:167], v[226:229], v[92:95]
	v_mfma_f32_16x16x32_bf16 v[88:91], v[186:189], v[226:229], v[88:91]
	v_mfma_f32_16x16x32_bf16 v[76:79], v[164:167], v[242:245], v[76:79]
	v_mfma_f32_16x16x32_bf16 v[72:75], v[186:189], v[242:245], v[72:75]
	s_setprio 0
	s_setprio 1
	v_mfma_f32_16x16x32_bf16 v[118:121], v[190:193], v[206:209], v[118:121]
	v_mfma_f32_16x16x32_bf16 v[114:117], v[198:201], v[206:209], v[114:117]
	v_mfma_f32_16x16x32_bf16 v[102:105], v[190:193], v[214:217], v[102:105]
	v_mfma_f32_16x16x32_bf16 v[98:101], v[198:201], v[214:217], v[98:101]
	v_mfma_f32_16x16x32_bf16 v[84:87], v[190:193], v[222:225], v[84:87]
	v_mfma_f32_16x16x32_bf16 v[80:83], v[198:201], v[222:225], v[80:83]
	v_mfma_f32_16x16x32_bf16 v[68:71], v[190:193], v[230:233], v[68:71]
	v_mfma_f32_16x16x32_bf16 v[64:67], v[198:201], v[230:233], v[64:67]
	v_mfma_f32_16x16x32_bf16 v[118:121], v[194:197], v[210:213], v[118:121]
	v_mfma_f32_16x16x32_bf16 v[114:117], v[202:205], v[210:213], v[114:117]
	v_mfma_f32_16x16x32_bf16 v[102:105], v[194:197], v[218:221], v[102:105]
	v_mfma_f32_16x16x32_bf16 v[98:101], v[202:205], v[218:221], v[98:101]
	v_mfma_f32_16x16x32_bf16 v[84:87], v[194:197], v[226:229], v[84:87]
	v_mfma_f32_16x16x32_bf16 v[80:83], v[202:205], v[226:229], v[80:83]
	v_mfma_f32_16x16x32_bf16 v[68:71], v[194:197], v[242:245], v[68:71]
	v_mfma_f32_16x16x32_bf16 v[64:67], v[202:205], v[242:245], v[64:67]
	s_setprio 0
	s_barrier
	s_setprio 3
	s_add_i32 s60, s60, s40
	v_lshl_add_u64 v[148:149], s[30:31], 0, v[134:135]
	s_mov_b32 m0, s60
	ds_read_b128 v[206:209], v163 offset:16384
	ds_read_b128 v[210:213], v163 offset:17408
	ds_read_b128 v[214:217], v163 offset:18432
	ds_read_b128 v[218:221], v163 offset:19456
	ds_read_b128 v[222:225], v163 offset:20480
	ds_read_b128 v[226:229], v163 offset:21504
	ds_read_b128 v[230:233], v163 offset:22528
	ds_read_b128 v[242:245], v163 offset:23552
	global_load_lds_dwordx4 v[148:149], off
	s_add_i32 m0, s60, 0x2000
	s_add_u32 s60, s30, 0x40000
	v_lshl_add_u64 v[154:155], s[30:31], 0, v[130:131]
	s_addc_u32 s61, s31, 0
	s_add_i32 s62, s62, s40
	global_load_lds_dwordx4 v[154:155], off
	v_lshl_add_u64 v[156:157], s[60:61], 0, v[134:135]
	s_mov_b32 m0, s62
	v_lshl_add_u64 v[158:159], s[34:35], 0, v[132:133]
	global_load_lds_dwordx4 v[156:157], off
	v_lshl_add_u64 v[156:157], s[60:61], 0, v[130:131]
	s_add_i32 m0, s62, 0x2000
	s_nop 0
	global_load_lds_dwordx4 v[156:157], off
	v_lshl_add_u64 v[156:157], s[34:35], 0, v[136:137]
	s_mov_b32 m0, s41
	s_nop 0
	global_load_lds_dwordx4 v[156:157], off
	s_mov_b32 m0, s42
	s_nop 0
	global_load_lds_dwordx4 v[158:159], off
	s_setprio 0
	s_waitcnt vmcnt(8)
	s_waitcnt lgkmcnt(0)
	s_barrier
	s_setprio 1
	v_mfma_f32_16x16x32_bf16 v[60:63], v[144:147], v[206:209], v[60:63]
	v_mfma_f32_16x16x32_bf16 v[56:59], v[168:171], v[206:209], v[56:59]
	v_mfma_f32_16x16x32_bf16 v[44:47], v[144:147], v[214:217], v[44:47]
	v_mfma_f32_16x16x32_bf16 v[40:43], v[168:171], v[214:217], v[40:43]
	v_mfma_f32_16x16x32_bf16 v[28:31], v[144:147], v[222:225], v[28:31]
	v_mfma_f32_16x16x32_bf16 v[24:27], v[168:171], v[222:225], v[24:27]
	v_mfma_f32_16x16x32_bf16 v[12:15], v[144:147], v[230:233], v[12:15]
	v_mfma_f32_16x16x32_bf16 v[8:11], v[168:171], v[230:233], v[8:11]
	v_mfma_f32_16x16x32_bf16 v[60:63], v[164:167], v[210:213], v[60:63]
	v_mfma_f32_16x16x32_bf16 v[56:59], v[186:189], v[210:213], v[56:59]
	v_mfma_f32_16x16x32_bf16 v[44:47], v[164:167], v[218:221], v[44:47]
	v_mfma_f32_16x16x32_bf16 v[40:43], v[186:189], v[218:221], v[40:43]
	v_mfma_f32_16x16x32_bf16 v[28:31], v[164:167], v[226:229], v[28:31]
	v_mfma_f32_16x16x32_bf16 v[24:27], v[186:189], v[226:229], v[24:27]
	v_mfma_f32_16x16x32_bf16 v[12:15], v[164:167], v[242:245], v[12:15]
	v_mfma_f32_16x16x32_bf16 v[8:11], v[186:189], v[242:245], v[8:11]
	s_setprio 0
	s_setprio 1
	v_mfma_f32_16x16x32_bf16 v[52:55], v[190:193], v[206:209], v[52:55]
	v_mfma_f32_16x16x32_bf16 v[48:51], v[198:201], v[206:209], v[48:51]
	v_mfma_f32_16x16x32_bf16 v[36:39], v[190:193], v[214:217], v[36:39]
	v_mfma_f32_16x16x32_bf16 v[32:35], v[198:201], v[214:217], v[32:35]
	v_mfma_f32_16x16x32_bf16 v[20:23], v[190:193], v[222:225], v[20:23]
	v_mfma_f32_16x16x32_bf16 v[16:19], v[198:201], v[222:225], v[16:19]
	v_mfma_f32_16x16x32_bf16 v[4:7], v[190:193], v[230:233], v[4:7]
	v_mfma_f32_16x16x32_bf16 v[0:3], v[198:201], v[230:233], v[0:3]
	v_mfma_f32_16x16x32_bf16 v[52:55], v[194:197], v[210:213], v[52:55]
	v_mfma_f32_16x16x32_bf16 v[48:51], v[202:205], v[210:213], v[48:51]
	v_mfma_f32_16x16x32_bf16 v[36:39], v[194:197], v[218:221], v[36:39]
	v_mfma_f32_16x16x32_bf16 v[32:35], v[202:205], v[218:221], v[32:35]
	v_mfma_f32_16x16x32_bf16 v[20:23], v[194:197], v[226:229], v[20:23]
	v_mfma_f32_16x16x32_bf16 v[16:19], v[202:205], v[226:229], v[16:19]
	v_mfma_f32_16x16x32_bf16 v[4:7], v[194:197], v[242:245], v[4:7]
	v_mfma_f32_16x16x32_bf16 v[0:3], v[202:205], v[242:245], v[0:3]
	s_setprio 0
	s_barrier
	s_setprio 3
	s_add_i32 s60, 0, 0x18000
	v_add_u32_e32 v96, s60, v151
	s_add_i32 s61, 0, 0x1c000
	ds_read_b128 v[144:147], v96
	ds_read_b128 v[164:167], v96 offset:1024
	ds_read_b128 v[168:171], v96 offset:2048
	ds_read_b128 v[186:189], v96 offset:3072
	v_add_u32_e32 v96, s61, v151
	ds_read_b128 v[190:193], v96
	ds_read_b128 v[194:197], v96 offset:1024
	ds_read_b128 v[198:201], v96 offset:2048
	ds_read_b128 v[202:205], v96 offset:3072
	s_add_u32 s34, s34, 0x40000
	s_addc_u32 s35, s35, 0
	s_mov_b32 m0, s43
	v_lshl_add_u64 v[172:173], s[34:35], 0, v[136:137]
	ds_read_b128 v[206:209], v163 offset:32768
	ds_read_b128 v[210:213], v163 offset:33792
	ds_read_b128 v[214:217], v163 offset:34816
	ds_read_b128 v[218:221], v163 offset:35840
	ds_read_b128 v[222:225], v163 offset:36864
	ds_read_b128 v[226:229], v163 offset:37888
	ds_read_b128 v[230:233], v163 offset:38912
	ds_read_b128 v[242:245], v163 offset:39936
	global_load_lds_dwordx4 v[172:173], off
	v_lshl_add_u64 v[172:173], s[34:35], 0, v[132:133]
	s_mov_b32 m0, s44
	s_nop 0
	global_load_lds_dwordx4 v[172:173], off
	s_setprio 0
	s_waitcnt vmcnt(8)
	s_waitcnt lgkmcnt(0)
	s_barrier
	s_setprio 1
	v_mfma_f32_16x16x32_bf16 v[126:129], v[144:147], v[206:209], v[126:129]
	v_mfma_f32_16x16x32_bf16 v[122:125], v[168:171], v[206:209], v[122:125]
	v_mfma_f32_16x16x32_bf16 v[110:113], v[144:147], v[214:217], v[110:113]
	v_mfma_f32_16x16x32_bf16 v[106:109], v[168:171], v[214:217], v[106:109]
	v_mfma_f32_16x16x32_bf16 v[92:95], v[144:147], v[222:225], v[92:95]
	v_mfma_f32_16x16x32_bf16 v[88:91], v[168:171], v[222:225], v[88:91]
	v_mfma_f32_16x16x32_bf16 v[76:79], v[144:147], v[230:233], v[76:79]
	v_mfma_f32_16x16x32_bf16 v[72:75], v[168:171], v[230:233], v[72:75]
	v_mfma_f32_16x16x32_bf16 v[126:129], v[164:167], v[210:213], v[126:129]
	v_mfma_f32_16x16x32_bf16 v[122:125], v[186:189], v[210:213], v[122:125]
	v_mfma_f32_16x16x32_bf16 v[110:113], v[164:167], v[218:221], v[110:113]
	v_mfma_f32_16x16x32_bf16 v[106:109], v[186:189], v[218:221], v[106:109]
	v_mfma_f32_16x16x32_bf16 v[92:95], v[164:167], v[226:229], v[92:95]
	v_mfma_f32_16x16x32_bf16 v[88:91], v[186:189], v[226:229], v[88:91]
	v_mfma_f32_16x16x32_bf16 v[76:79], v[164:167], v[242:245], v[76:79]
	v_mfma_f32_16x16x32_bf16 v[72:75], v[186:189], v[242:245], v[72:75]
	s_setprio 0
	s_setprio 1
	v_mfma_f32_16x16x32_bf16 v[118:121], v[190:193], v[206:209], v[118:121]
	v_mfma_f32_16x16x32_bf16 v[114:117], v[198:201], v[206:209], v[114:117]
	v_mfma_f32_16x16x32_bf16 v[102:105], v[190:193], v[214:217], v[102:105]
	v_mfma_f32_16x16x32_bf16 v[98:101], v[198:201], v[214:217], v[98:101]
	v_mfma_f32_16x16x32_bf16 v[84:87], v[190:193], v[222:225], v[84:87]
	v_mfma_f32_16x16x32_bf16 v[80:83], v[198:201], v[222:225], v[80:83]
	v_mfma_f32_16x16x32_bf16 v[68:71], v[190:193], v[230:233], v[68:71]
	v_mfma_f32_16x16x32_bf16 v[64:67], v[198:201], v[230:233], v[64:67]
	v_mfma_f32_16x16x32_bf16 v[118:121], v[194:197], v[210:213], v[118:121]
	v_mfma_f32_16x16x32_bf16 v[114:117], v[202:205], v[210:213], v[114:117]
	v_mfma_f32_16x16x32_bf16 v[102:105], v[194:197], v[218:221], v[102:105]
	v_mfma_f32_16x16x32_bf16 v[98:101], v[202:205], v[218:221], v[98:101]
	v_mfma_f32_16x16x32_bf16 v[84:87], v[194:197], v[226:229], v[84:87]
	v_mfma_f32_16x16x32_bf16 v[80:83], v[202:205], v[226:229], v[80:83]
	v_mfma_f32_16x16x32_bf16 v[68:71], v[194:197], v[242:245], v[68:71]
	v_mfma_f32_16x16x32_bf16 v[64:67], v[202:205], v[242:245], v[64:67]
	s_setprio 0
	s_barrier
	s_setprio 3
	s_add_i32 s34, s60, s40
	v_lshl_add_u64 v[148:149], v[148:149], 0, s[16:17]
	s_mov_b32 m0, s34
	ds_read_b128 v[206:209], v163 offset:49152
	ds_read_b128 v[210:213], v163 offset:50176
	ds_read_b128 v[214:217], v163 offset:51200
	ds_read_b128 v[218:221], v163 offset:52224
	ds_read_b128 v[222:225], v163 offset:53248
	ds_read_b128 v[226:229], v163 offset:54272
	ds_read_b128 v[230:233], v163 offset:55296
	ds_read_b128 v[242:245], v163 offset:56320
	global_load_lds_dwordx4 v[148:149], off
	s_add_i32 m0, s34, 0x2000
	s_add_u32 s30, s30, 0x40080
	v_lshl_add_u64 v[148:149], v[154:155], 0, s[16:17]
	s_addc_u32 s31, s31, 0
	s_add_i32 s34, s61, s40
	global_load_lds_dwordx4 v[148:149], off
	v_lshl_add_u64 v[148:149], s[30:31], 0, v[134:135]
	s_mov_b32 m0, s34
	s_nop 0
	global_load_lds_dwordx4 v[148:149], off
	v_lshl_add_u64 v[148:149], s[30:31], 0, v[130:131]
	s_add_i32 m0, s34, 0x2000
	s_nop 0
	global_load_lds_dwordx4 v[148:149], off
	v_lshl_add_u64 v[148:149], v[156:157], 0, s[16:17]
	s_mov_b32 m0, s49
	s_nop 0
	global_load_lds_dwordx4 v[148:149], off
	v_lshl_add_u64 v[148:149], v[158:159], 0, s[16:17]
	s_mov_b32 m0, s50
	s_nop 0
	global_load_lds_dwordx4 v[148:149], off
	s_setprio 0
	s_waitcnt vmcnt(8)
	s_waitcnt lgkmcnt(0)
	s_barrier
	s_setprio 1
	v_mfma_f32_16x16x32_bf16 v[60:63], v[144:147], v[206:209], v[60:63]
	v_mfma_f32_16x16x32_bf16 v[56:59], v[168:171], v[206:209], v[56:59]
	v_mfma_f32_16x16x32_bf16 v[44:47], v[144:147], v[214:217], v[44:47]
	v_mfma_f32_16x16x32_bf16 v[40:43], v[168:171], v[214:217], v[40:43]
	v_mfma_f32_16x16x32_bf16 v[28:31], v[144:147], v[222:225], v[28:31]
	v_mfma_f32_16x16x32_bf16 v[24:27], v[168:171], v[222:225], v[24:27]
	v_mfma_f32_16x16x32_bf16 v[12:15], v[144:147], v[230:233], v[12:15]
	v_mfma_f32_16x16x32_bf16 v[8:11], v[168:171], v[230:233], v[8:11]
	v_mfma_f32_16x16x32_bf16 v[60:63], v[164:167], v[210:213], v[60:63]
	v_mfma_f32_16x16x32_bf16 v[56:59], v[186:189], v[210:213], v[56:59]
	v_mfma_f32_16x16x32_bf16 v[44:47], v[164:167], v[218:221], v[44:47]
	v_mfma_f32_16x16x32_bf16 v[40:43], v[186:189], v[218:221], v[40:43]
	v_mfma_f32_16x16x32_bf16 v[28:31], v[164:167], v[226:229], v[28:31]
	v_mfma_f32_16x16x32_bf16 v[24:27], v[186:189], v[226:229], v[24:27]
	v_mfma_f32_16x16x32_bf16 v[12:15], v[164:167], v[242:245], v[12:15]
	v_mfma_f32_16x16x32_bf16 v[8:11], v[186:189], v[242:245], v[8:11]
	s_setprio 0
	s_setprio 1
	v_mfma_f32_16x16x32_bf16 v[52:55], v[190:193], v[206:209], v[52:55]
	v_mfma_f32_16x16x32_bf16 v[48:51], v[198:201], v[206:209], v[48:51]
	v_mfma_f32_16x16x32_bf16 v[36:39], v[190:193], v[214:217], v[36:39]
	v_mfma_f32_16x16x32_bf16 v[32:35], v[198:201], v[214:217], v[32:35]
	v_mfma_f32_16x16x32_bf16 v[20:23], v[190:193], v[222:225], v[20:23]
	v_mfma_f32_16x16x32_bf16 v[16:19], v[198:201], v[222:225], v[16:19]
	v_mfma_f32_16x16x32_bf16 v[4:7], v[190:193], v[230:233], v[4:7]
	v_mfma_f32_16x16x32_bf16 v[0:3], v[198:201], v[230:233], v[0:3]
	v_mfma_f32_16x16x32_bf16 v[52:55], v[194:197], v[210:213], v[52:55]
	v_mfma_f32_16x16x32_bf16 v[48:51], v[202:205], v[210:213], v[48:51]
	v_mfma_f32_16x16x32_bf16 v[36:39], v[194:197], v[218:221], v[36:39]
	v_mfma_f32_16x16x32_bf16 v[32:35], v[202:205], v[218:221], v[32:35]
	v_mfma_f32_16x16x32_bf16 v[20:23], v[194:197], v[226:229], v[20:23]
	v_mfma_f32_16x16x32_bf16 v[16:19], v[202:205], v[226:229], v[16:19]
	v_mfma_f32_16x16x32_bf16 v[4:7], v[194:197], v[242:245], v[4:7]
	v_mfma_f32_16x16x32_bf16 v[0:3], v[202:205], v[242:245], v[0:3]
	s_setprio 0
	s_barrier
	s_setprio 3
	s_add_i32 s59, s59, 2
	s_add_u32 s14, s14, 0x100
	s_addc_u32 s15, s15, 0
	s_add_u32 s57, s57, 0x100
	s_addc_u32 s58, s58, 0
	s_cmp_gt_u32 s59, 13
	s_cbranch_scc0 .LBB0_449
	s_and_b64 vcc, exec, s[18:19]
	s_cbranch_vccz .LBB0_454
	s_barrier
	v_lshl_add_u32 v146, s54, 8, v150
	s_cmp_gt_i32 s53, 7
	s_mov_b64 s[14:15], -1
	s_cbranch_scc1 .LBB0_455

.LBB0_490:
	s_add_i32 s66, s6, 2
	s_add_u32 s67, s4, 0x80
	s_addc_u32 s7, s5, 0
	s_add_i32 s70, 0, 0x10000
	s_cmp_eq_u32 s60, s6
	s_cselect_b32 s7, s43, s7
	s_cselect_b32 s6, s42, s67
	v_add_u32_e32 v148, s70, v151
	s_cselect_b32 s69, s45, s15
	s_cselect_b32 s68, s44, s14
	s_add_i32 s67, 0, 0x14000
	ds_read_b128 v[140:143], v148
	ds_read_b128 v[144:147], v148 offset:1024
	ds_read_b128 v[162:165], v148 offset:2048
	ds_read_b128 v[166:169], v148 offset:3072
	v_add_u32_e32 v148, s67, v151
	ds_read_b128 v[170:173], v148
	ds_read_b128 v[186:189], v148 offset:1024
	ds_read_b128 v[190:193], v148 offset:2048
	ds_read_b128 v[194:197], v148 offset:3072
	v_lshl_add_u64 v[148:149], s[4:5], 0, v[136:137]
	s_add_i32 m0, s52, 0xc000
	ds_read_b128 v[198:201], v153
	ds_read_b128 v[202:205], v153 offset:1024
	ds_read_b128 v[206:209], v153 offset:2048
	ds_read_b128 v[210:213], v153 offset:3072
	ds_read_b128 v[214:217], v153 offset:4096
	ds_read_b128 v[218:221], v153 offset:5120
	ds_read_b128 v[222:225], v153 offset:6144
	ds_read_b128 v[226:229], v153 offset:7168
	global_load_lds_dwordx4 v[148:149], off
	v_lshl_add_u64 v[148:149], s[4:5], 0, v[138:139]
	s_add_i32 m0, s52, 0xe000
	s_nop 0
	global_load_lds_dwordx4 v[148:149], off
	s_setprio 0
	s_waitcnt vmcnt(8)
	s_waitcnt lgkmcnt(0)
	s_barrier
	s_setprio 1
	v_mfma_f32_16x16x32_bf16 v[126:129], v[140:143], v[198:201], v[126:129]
	v_mfma_f32_16x16x32_bf16 v[122:125], v[162:165], v[198:201], v[122:125]
	v_mfma_f32_16x16x32_bf16 v[110:113], v[140:143], v[206:209], v[110:113]
	v_mfma_f32_16x16x32_bf16 v[106:109], v[162:165], v[206:209], v[106:109]
	v_mfma_f32_16x16x32_bf16 v[92:95], v[140:143], v[214:217], v[92:95]
	v_mfma_f32_16x16x32_bf16 v[88:91], v[162:165], v[214:217], v[88:91]
	v_mfma_f32_16x16x32_bf16 v[76:79], v[140:143], v[222:225], v[76:79]
	v_mfma_f32_16x16x32_bf16 v[72:75], v[162:165], v[222:225], v[72:75]
	v_mfma_f32_16x16x32_bf16 v[126:129], v[144:147], v[202:205], v[126:129]
	v_mfma_f32_16x16x32_bf16 v[122:125], v[166:169], v[202:205], v[122:125]
	v_mfma_f32_16x16x32_bf16 v[110:113], v[144:147], v[210:213], v[110:113]
	v_mfma_f32_16x16x32_bf16 v[106:109], v[166:169], v[210:213], v[106:109]
	v_mfma_f32_16x16x32_bf16 v[92:95], v[144:147], v[218:221], v[92:95]
	v_mfma_f32_16x16x32_bf16 v[88:91], v[166:169], v[218:221], v[88:91]
	v_mfma_f32_16x16x32_bf16 v[76:79], v[144:147], v[226:229], v[76:79]
	v_mfma_f32_16x16x32_bf16 v[72:75], v[166:169], v[226:229], v[72:75]
	s_setprio 0
	s_setprio 1
	v_mfma_f32_16x16x32_bf16 v[118:121], v[170:173], v[198:201], v[118:121]
	v_mfma_f32_16x16x32_bf16 v[114:117], v[190:193], v[198:201], v[114:117]
	v_mfma_f32_16x16x32_bf16 v[102:105], v[170:173], v[206:209], v[102:105]
	v_mfma_f32_16x16x32_bf16 v[98:101], v[190:193], v[206:209], v[98:101]
	v_mfma_f32_16x16x32_bf16 v[84:87], v[170:173], v[214:217], v[84:87]
	v_mfma_f32_16x16x32_bf16 v[80:83], v[190:193], v[214:217], v[80:83]
	v_mfma_f32_16x16x32_bf16 v[68:71], v[170:173], v[222:225], v[68:71]
	v_mfma_f32_16x16x32_bf16 v[64:67], v[190:193], v[222:225], v[64:67]
	v_mfma_f32_16x16x32_bf16 v[118:121], v[186:189], v[202:205], v[118:121]
	v_mfma_f32_16x16x32_bf16 v[114:117], v[194:197], v[202:205], v[114:117]
	v_mfma_f32_16x16x32_bf16 v[102:105], v[186:189], v[210:213], v[102:105]
	v_mfma_f32_16x16x32_bf16 v[98:101], v[194:197], v[210:213], v[98:101]
	v_mfma_f32_16x16x32_bf16 v[84:87], v[186:189], v[218:221], v[84:87]
	v_mfma_f32_16x16x32_bf16 v[80:83], v[194:197], v[218:221], v[80:83]
	v_mfma_f32_16x16x32_bf16 v[68:71], v[186:189], v[226:229], v[68:71]
	v_mfma_f32_16x16x32_bf16 v[64:67], v[194:197], v[226:229], v[64:67]
	s_setprio 0
	s_barrier
	s_setprio 3
	s_add_i32 s70, s70, s51
	v_lshl_add_u64 v[148:149], s[68:69], 0, v[96:97]
	s_mov_b32 m0, s70
	ds_read_b128 v[198:201], v153 offset:16384
	ds_read_b128 v[202:205], v153 offset:17408
	ds_read_b128 v[206:209], v153 offset:18432
	ds_read_b128 v[210:213], v153 offset:19456
	ds_read_b128 v[214:217], v153 offset:20480
	ds_read_b128 v[218:221], v153 offset:21504
	ds_read_b128 v[222:225], v153 offset:22528
	ds_read_b128 v[226:229], v153 offset:23552
	global_load_lds_dwordx4 v[148:149], off
	s_add_i32 m0, s70, 0x2000
	v_lshl_add_u64 v[154:155], s[68:69], 0, v[130:131]
	s_add_u32 s68, s68, s46
	s_addc_u32 s69, s69, 0
	s_add_i32 s67, s67, s51
	global_load_lds_dwordx4 v[154:155], off
	v_lshl_add_u64 v[156:157], s[68:69], 0, v[96:97]
	s_mov_b32 m0, s67
	v_lshl_add_u64 v[158:159], s[68:69], 0, v[130:131]
	global_load_lds_dwordx4 v[156:157], off
	s_add_i32 m0, s67, 0x2000
	v_lshl_add_u64 v[182:183], s[6:7], 0, v[134:135]
	global_load_lds_dwordx4 v[158:159], off
	s_mov_b32 m0, s52
	v_lshl_add_u64 v[184:185], s[6:7], 0, v[132:133]
	global_load_lds_dwordx4 v[182:183], off
	s_mov_b32 m0, s53
	s_nop 0
	global_load_lds_dwordx4 v[184:185], off
	s_setprio 0
	s_waitcnt vmcnt(8)
	s_waitcnt lgkmcnt(0)
	s_barrier
	s_setprio 1
	v_mfma_f32_16x16x32_bf16 v[60:63], v[140:143], v[198:201], v[60:63]
	v_mfma_f32_16x16x32_bf16 v[56:59], v[162:165], v[198:201], v[56:59]
	v_mfma_f32_16x16x32_bf16 v[44:47], v[140:143], v[206:209], v[44:47]
	v_mfma_f32_16x16x32_bf16 v[40:43], v[162:165], v[206:209], v[40:43]
	v_mfma_f32_16x16x32_bf16 v[28:31], v[140:143], v[214:217], v[28:31]
	v_mfma_f32_16x16x32_bf16 v[24:27], v[162:165], v[214:217], v[24:27]
	v_mfma_f32_16x16x32_bf16 v[12:15], v[140:143], v[222:225], v[12:15]
	v_mfma_f32_16x16x32_bf16 v[8:11], v[162:165], v[222:225], v[8:11]
	v_mfma_f32_16x16x32_bf16 v[60:63], v[144:147], v[202:205], v[60:63]
	v_mfma_f32_16x16x32_bf16 v[56:59], v[166:169], v[202:205], v[56:59]
	v_mfma_f32_16x16x32_bf16 v[44:47], v[144:147], v[210:213], v[44:47]
	v_mfma_f32_16x16x32_bf16 v[40:43], v[166:169], v[210:213], v[40:43]
	v_mfma_f32_16x16x32_bf16 v[28:31], v[144:147], v[218:221], v[28:31]
	v_mfma_f32_16x16x32_bf16 v[24:27], v[166:169], v[218:221], v[24:27]
	v_mfma_f32_16x16x32_bf16 v[12:15], v[144:147], v[226:229], v[12:15]
	v_mfma_f32_16x16x32_bf16 v[8:11], v[166:169], v[226:229], v[8:11]
	s_setprio 0
	s_setprio 1
	v_mfma_f32_16x16x32_bf16 v[52:55], v[170:173], v[198:201], v[52:55]
	v_mfma_f32_16x16x32_bf16 v[48:51], v[190:193], v[198:201], v[48:51]
	v_mfma_f32_16x16x32_bf16 v[36:39], v[170:173], v[206:209], v[36:39]
	v_mfma_f32_16x16x32_bf16 v[32:35], v[190:193], v[206:209], v[32:35]
	v_mfma_f32_16x16x32_bf16 v[20:23], v[170:173], v[214:217], v[20:23]
	v_mfma_f32_16x16x32_bf16 v[16:19], v[190:193], v[214:217], v[16:19]
	v_mfma_f32_16x16x32_bf16 v[4:7], v[170:173], v[222:225], v[4:7]
	v_mfma_f32_16x16x32_bf16 v[0:3], v[190:193], v[222:225], v[0:3]
	v_mfma_f32_16x16x32_bf16 v[52:55], v[186:189], v[202:205], v[52:55]
	v_mfma_f32_16x16x32_bf16 v[48:51], v[194:197], v[202:205], v[48:51]
	v_mfma_f32_16x16x32_bf16 v[36:39], v[186:189], v[210:213], v[36:39]
	v_mfma_f32_16x16x32_bf16 v[32:35], v[194:197], v[210:213], v[32:35]
	v_mfma_f32_16x16x32_bf16 v[20:23], v[186:189], v[218:221], v[20:23]
	v_mfma_f32_16x16x32_bf16 v[16:19], v[194:197], v[218:221], v[16:19]
	v_mfma_f32_16x16x32_bf16 v[4:7], v[186:189], v[226:229], v[4:7]
	v_mfma_f32_16x16x32_bf16 v[0:3], v[194:197], v[226:229], v[0:3]
	s_setprio 0
	s_barrier
	s_setprio 3
	s_add_i32 s67, 0, 0x18000
	s_add_i32 s68, 0, 0x1c000
	v_add_u32_e32 v166, s67, v151
	v_add_u32_e32 v194, s68, v151
	ds_read_b128 v[140:143], v166
	ds_read_b128 v[144:147], v166 offset:1024
	ds_read_b128 v[162:165], v166 offset:2048
	ds_read_b128 v[166:169], v166 offset:3072
	ds_read_b128 v[170:173], v194
	ds_read_b128 v[186:189], v194 offset:1024
	ds_read_b128 v[190:193], v194 offset:2048
	ds_read_b128 v[194:197], v194 offset:3072
	s_add_u32 s6, s6, s46
	s_addc_u32 s7, s7, 0
	s_mov_b32 m0, s54
	v_lshl_add_u64 v[230:231], s[6:7], 0, v[134:135]
	ds_read_b128 v[198:201], v153 offset:32768
	ds_read_b128 v[202:205], v153 offset:33792
	ds_read_b128 v[206:209], v153 offset:34816
	ds_read_b128 v[210:213], v153 offset:35840
	ds_read_b128 v[214:217], v153 offset:36864
	ds_read_b128 v[218:221], v153 offset:37888
	ds_read_b128 v[222:225], v153 offset:38912
	ds_read_b128 v[226:229], v153 offset:39936
	global_load_lds_dwordx4 v[230:231], off
	v_lshl_add_u64 v[230:231], s[6:7], 0, v[132:133]
	s_mov_b32 m0, s55
	s_nop 0
	global_load_lds_dwordx4 v[230:231], off
	s_setprio 0
	s_waitcnt vmcnt(8)
	s_waitcnt lgkmcnt(0)
	s_barrier
	s_setprio 1
	v_mfma_f32_16x16x32_bf16 v[126:129], v[140:143], v[198:201], v[126:129]
	v_mfma_f32_16x16x32_bf16 v[122:125], v[162:165], v[198:201], v[122:125]
	v_mfma_f32_16x16x32_bf16 v[110:113], v[140:143], v[206:209], v[110:113]
	v_mfma_f32_16x16x32_bf16 v[106:109], v[162:165], v[206:209], v[106:109]
	v_mfma_f32_16x16x32_bf16 v[92:95], v[140:143], v[214:217], v[92:95]
	v_mfma_f32_16x16x32_bf16 v[88:91], v[162:165], v[214:217], v[88:91]
	v_mfma_f32_16x16x32_bf16 v[76:79], v[140:143], v[222:225], v[76:79]
	v_mfma_f32_16x16x32_bf16 v[72:75], v[162:165], v[222:225], v[72:75]
	v_mfma_f32_16x16x32_bf16 v[126:129], v[144:147], v[202:205], v[126:129]
	v_mfma_f32_16x16x32_bf16 v[122:125], v[166:169], v[202:205], v[122:125]
	v_mfma_f32_16x16x32_bf16 v[110:113], v[144:147], v[210:213], v[110:113]
	v_mfma_f32_16x16x32_bf16 v[106:109], v[166:169], v[210:213], v[106:109]
	v_mfma_f32_16x16x32_bf16 v[92:95], v[144:147], v[218:221], v[92:95]
	v_mfma_f32_16x16x32_bf16 v[88:91], v[166:169], v[218:221], v[88:91]
	v_mfma_f32_16x16x32_bf16 v[76:79], v[144:147], v[226:229], v[76:79]
	v_mfma_f32_16x16x32_bf16 v[72:75], v[166:169], v[226:229], v[72:75]
	s_setprio 0
	s_setprio 1
	v_mfma_f32_16x16x32_bf16 v[118:121], v[170:173], v[198:201], v[118:121]
	v_mfma_f32_16x16x32_bf16 v[114:117], v[190:193], v[198:201], v[114:117]
	v_mfma_f32_16x16x32_bf16 v[102:105], v[170:173], v[206:209], v[102:105]
	v_mfma_f32_16x16x32_bf16 v[98:101], v[190:193], v[206:209], v[98:101]
	v_mfma_f32_16x16x32_bf16 v[84:87], v[170:173], v[214:217], v[84:87]
	v_mfma_f32_16x16x32_bf16 v[80:83], v[190:193], v[214:217], v[80:83]
	v_mfma_f32_16x16x32_bf16 v[68:71], v[170:173], v[222:225], v[68:71]
	v_mfma_f32_16x16x32_bf16 v[64:67], v[190:193], v[222:225], v[64:67]
	v_mfma_f32_16x16x32_bf16 v[118:121], v[186:189], v[202:205], v[118:121]
	v_mfma_f32_16x16x32_bf16 v[114:117], v[194:197], v[202:205], v[114:117]
	v_mfma_f32_16x16x32_bf16 v[102:105], v[186:189], v[210:213], v[102:105]
	v_mfma_f32_16x16x32_bf16 v[98:101], v[194:197], v[210:213], v[98:101]
	v_mfma_f32_16x16x32_bf16 v[84:87], v[186:189], v[218:221], v[84:87]
	v_mfma_f32_16x16x32_bf16 v[80:83], v[194:197], v[218:221], v[80:83]
	v_mfma_f32_16x16x32_bf16 v[68:71], v[186:189], v[226:229], v[68:71]
	v_mfma_f32_16x16x32_bf16 v[64:67], v[194:197], v[226:229], v[64:67]
	s_setprio 0
	s_barrier
	s_setprio 3
	s_add_i32 s6, s67, s51
	v_lshl_add_u64 v[148:149], v[148:149], 0, s[16:17]
	s_mov_b32 m0, s6
	ds_read_b128 v[198:201], v153 offset:49152
	ds_read_b128 v[202:205], v153 offset:50176
	ds_read_b128 v[206:209], v153 offset:51200
	ds_read_b128 v[210:213], v153 offset:52224
	ds_read_b128 v[214:217], v153 offset:53248
	ds_read_b128 v[218:221], v153 offset:54272
	ds_read_b128 v[222:225], v153 offset:55296
	ds_read_b128 v[226:229], v153 offset:56320
	global_load_lds_dwordx4 v[148:149], off
	v_lshl_add_u64 v[148:149], v[154:155], 0, s[16:17]
	s_add_i32 m0, s6, 0x2000
	s_add_i32 s6, s68, s51
	global_load_lds_dwordx4 v[148:149], off
	v_lshl_add_u64 v[148:149], v[156:157], 0, s[16:17]
	s_mov_b32 m0, s6
	s_nop 0
	global_load_lds_dwordx4 v[148:149], off
	v_lshl_add_u64 v[148:149], v[158:159], 0, s[16:17]
	s_add_i32 m0, s6, 0x2000
	s_nop 0
	global_load_lds_dwordx4 v[148:149], off
	v_lshl_add_u64 v[148:149], v[182:183], 0, s[16:17]
	s_mov_b32 m0, s56
	s_nop 0
	global_load_lds_dwordx4 v[148:149], off
	v_lshl_add_u64 v[148:149], v[184:185], 0, s[16:17]
	s_mov_b32 m0, s57
	s_nop 0
	global_load_lds_dwordx4 v[148:149], off
	s_setprio 0
	s_waitcnt vmcnt(8)
	s_waitcnt lgkmcnt(0)
	s_barrier
	s_setprio 1
	v_mfma_f32_16x16x32_bf16 v[60:63], v[140:143], v[198:201], v[60:63]
	v_mfma_f32_16x16x32_bf16 v[56:59], v[162:165], v[198:201], v[56:59]
	v_mfma_f32_16x16x32_bf16 v[44:47], v[140:143], v[206:209], v[44:47]
	v_mfma_f32_16x16x32_bf16 v[40:43], v[162:165], v[206:209], v[40:43]
	v_mfma_f32_16x16x32_bf16 v[28:31], v[140:143], v[214:217], v[28:31]
	v_mfma_f32_16x16x32_bf16 v[24:27], v[162:165], v[214:217], v[24:27]
	v_mfma_f32_16x16x32_bf16 v[12:15], v[140:143], v[222:225], v[12:15]
	v_mfma_f32_16x16x32_bf16 v[8:11], v[162:165], v[222:225], v[8:11]
	v_mfma_f32_16x16x32_bf16 v[60:63], v[144:147], v[202:205], v[60:63]
	v_mfma_f32_16x16x32_bf16 v[56:59], v[166:169], v[202:205], v[56:59]
	v_mfma_f32_16x16x32_bf16 v[44:47], v[144:147], v[210:213], v[44:47]
	v_mfma_f32_16x16x32_bf16 v[40:43], v[166:169], v[210:213], v[40:43]
	v_mfma_f32_16x16x32_bf16 v[28:31], v[144:147], v[218:221], v[28:31]
	v_mfma_f32_16x16x32_bf16 v[24:27], v[166:169], v[218:221], v[24:27]
	v_mfma_f32_16x16x32_bf16 v[12:15], v[144:147], v[226:229], v[12:15]
	v_mfma_f32_16x16x32_bf16 v[8:11], v[166:169], v[226:229], v[8:11]
	s_setprio 0
	s_setprio 1
	v_mfma_f32_16x16x32_bf16 v[52:55], v[170:173], v[198:201], v[52:55]
	v_mfma_f32_16x16x32_bf16 v[48:51], v[190:193], v[198:201], v[48:51]
	v_mfma_f32_16x16x32_bf16 v[36:39], v[170:173], v[206:209], v[36:39]
	v_mfma_f32_16x16x32_bf16 v[32:35], v[190:193], v[206:209], v[32:35]
	v_mfma_f32_16x16x32_bf16 v[20:23], v[170:173], v[214:217], v[20:23]
	v_mfma_f32_16x16x32_bf16 v[16:19], v[190:193], v[214:217], v[16:19]
	v_mfma_f32_16x16x32_bf16 v[4:7], v[170:173], v[222:225], v[4:7]
	v_mfma_f32_16x16x32_bf16 v[0:3], v[190:193], v[222:225], v[0:3]
	v_mfma_f32_16x16x32_bf16 v[52:55], v[186:189], v[202:205], v[52:55]
	v_mfma_f32_16x16x32_bf16 v[48:51], v[194:197], v[202:205], v[48:51]
	v_mfma_f32_16x16x32_bf16 v[36:39], v[186:189], v[210:213], v[36:39]
	v_mfma_f32_16x16x32_bf16 v[32:35], v[194:197], v[210:213], v[32:35]
	v_mfma_f32_16x16x32_bf16 v[20:23], v[186:189], v[218:221], v[20:23]
	v_mfma_f32_16x16x32_bf16 v[16:19], v[194:197], v[218:221], v[16:19]
	v_mfma_f32_16x16x32_bf16 v[4:7], v[186:189], v[226:229], v[4:7]
	v_mfma_f32_16x16x32_bf16 v[0:3], v[194:197], v[226:229], v[0:3]
	s_setprio 0
	s_barrier
	s_setprio 3
	s_add_u32 s4, s4, 0x100
	s_addc_u32 s5, s5, 0
	s_add_u32 s14, s14, 0x100
	s_addc_u32 s15, s15, 0
	s_cmp_ge_u32 s66, s59
	s_mov_b32 s6, s66
	s_cbranch_scc0 .LBB0_490
	s_and_b64 vcc, exec, s[36:37]
	s_cbranch_vccz .LBB0_493
	s_barrier
